# prologue: nt (streaming) policy on the once-read f32 weight loads of the transpose-convert items
# speedup vs baseline: 1.0216x; 1.0126x over previous
.LBB0_9:
	s_add_i32 s52, s11, 0x4500
	s_cmpk_gt_i32 s52, 0x7ff
	s_mov_b64 s[14:15], -1
	s_cbranch_scc0 .LBB0_57
	s_cmpk_gt_u32 s52, 0x87f
	s_cbranch_scc0 .LBB0_54
	s_cmpk_gt_u32 s52, 0x137f
	s_cbranch_scc0 .LBB0_49
	s_cmpk_gt_u32 s52, 0x1e7f
	s_cbranch_scc0 .LBB0_44
	s_cmpk_gt_u32 s52, 0x227f
	s_cbranch_scc0 .LBB0_41
	s_cmpk_gt_u32 s52, 0x2d7f
	s_cbranch_scc0 .LBB0_38
	s_cmpk_gt_u32 s52, 0x317f
	s_cbranch_scc0 .LBB0_33
	s_cmpk_gt_u32 s52, 0x357f
	s_cbranch_scc0 .LBB0_30
	s_cmpk_gt_u32 s52, 0x35ff
	s_cbranch_scc0 .LBB0_27
	s_cmpk_gt_u32 s52, 0x39ff
	s_cbranch_scc0 .LBB0_24
	s_cmpk_gt_u32 s52, 0x44ff
	s_cbranch_scc0 .LBB0_21
	s_and_b32 s4, s11, 0xffff
	s_mul_hi_u32 s16, s4, 0x2e8ba2f
	s_mov_b64 s[14:15], s[0:1]
	s_mul_i32 s4, s4, 0xba2f
	s_load_dwordx2 s[54:55], s[14:15], 0xb8
	s_lshr_b32 s4, s4, 22
	s_lshl_b32 s53, s4, 6
	v_or_b32_e32 v2, s53, v67
	s_mul_i32 s17, s16, 0xffffea00
	v_mul_u32_u24_e32 v2, 0x1600, v2
	s_add_i32 vcc_lo, s21, s17
	v_lshlrev_b32_e32 v70, 2, v2
	s_waitcnt lgkmcnt(0)
	v_lshl_add_u64 v[2:3], s[54:55], 0, v[70:71]
	s_ashr_i32 vcc_hi, vcc_lo, 31
	v_lshl_add_u64 v[2:3], vcc, 2, v[2:3]
	v_lshlrev_b32_e32 v70, 2, v68
	v_lshl_add_u64 v[62:63], v[2:3], 0, v[70:71]
	v_add_co_u32_e32 v2, vcc, s56, v62
	s_mov_b32 s17, 0x2c05000
	s_nop 0
	v_addc_co_u32_e32 v3, vcc, 0, v63, vcc
	v_add_co_u32_e32 v6, vcc, s17, v62
	s_mov_b32 s17, 0x2c2c000
	s_nop 0
	v_addc_co_u32_e32 v7, vcc, 0, v63, vcc
	v_add_co_u32_e32 v10, vcc, s17, v62
	s_mov_b32 s17, 0x2c31000
	s_nop 0
	v_addc_co_u32_e32 v11, vcc, 0, v63, vcc
	v_add_co_u32_e32 v14, vcc, s17, v62
	s_mov_b32 s17, 0x2c58000
	s_nop 0
	v_addc_co_u32_e32 v15, vcc, 0, v63, vcc
	v_add_co_u32_e32 v18, vcc, s17, v62
	s_mov_b32 s17, 0x2c5d000
	s_nop 0
	v_addc_co_u32_e32 v19, vcc, 0, v63, vcc
	v_add_co_u32_e32 v22, vcc, s17, v62
	s_mov_b32 s17, 0x2c84000
	s_nop 0
	v_addc_co_u32_e32 v23, vcc, 0, v63, vcc
	v_add_co_u32_e32 v26, vcc, s17, v62
	s_mov_b32 s17, 0x2c89000
	s_nop 0
	v_addc_co_u32_e32 v27, vcc, 0, v63, vcc
	v_add_co_u32_e32 v30, vcc, s17, v62
	s_mov_b32 s17, 0x2cb0000
	s_nop 0
	v_addc_co_u32_e32 v31, vcc, 0, v63, vcc
	s_mov_b64 s[14:15], s[0:1]
	v_add_co_u32_e32 v34, vcc, s17, v62
	s_load_dwordx2 s[14:15], s[14:15], 0x18
	s_nop 0
	v_addc_co_u32_e32 v35, vcc, 0, v63, vcc
	v_add_co_u32_e32 v38, vcc, s57, v62
	v_or_b32_e32 v44, s53, v93
	s_nop 0
	v_addc_co_u32_e32 v39, vcc, 0, v63, vcc
	v_add_co_u32_e32 v42, vcc, s58, v62
	v_lshlrev_b32_e32 v70, 2, v44
	s_nop 0
	v_addc_co_u32_e32 v43, vcc, 0, v63, vcc
	v_add_co_u32_e32 v46, vcc, s59, v62
	s_waitcnt lgkmcnt(0)
	v_lshl_add_u64 v[50:51], s[14:15], 0, v[70:71]
	v_addc_co_u32_e32 v47, vcc, 0, v63, vcc
	v_add_co_u32_e32 v44, vcc, s64, v50
	v_lshl_add_u64 v[64:65], v[50:51], 0, s[6:7]
	s_nop 0
	v_addc_co_u32_e32 v45, vcc, 0, v51, vcc
	v_add_co_u32_e32 v50, vcc, s60, v62
	global_load_dwordx4 v[2:5], v[2:3], off nt
	s_nop 0
	global_load_dwordx4 v[6:9], v[6:7], off offset:2048 nt
	v_addc_co_u32_e32 v51, vcc, 0, v63, vcc
	global_load_dwordx4 v[10:13], v[10:11], off nt
	s_nop 0
	global_load_dwordx4 v[14:17], v[14:15], off offset:2048 nt
	s_nop 0
	global_load_dwordx4 v[18:21], v[18:19], off nt
	s_nop 0
	global_load_dwordx4 v[22:25], v[22:23], off offset:2048 nt
	s_nop 0
	global_load_dwordx4 v[26:29], v[26:27], off nt
	s_nop 0
	global_load_dwordx4 v[30:33], v[30:31], off offset:2048 nt
	s_nop 0
	global_load_dwordx4 v[34:37], v[34:35], off nt
	s_nop 0
	global_load_dwordx4 v[38:41], v[38:39], off offset:2048 nt
	s_nop 0
	global_load_dwordx2 v[148:149], v[44:45], off
	s_nop 0
	global_load_dwordx4 v[42:45], v[42:43], off nt
	s_nop 0
	global_load_dwordx4 v[46:49], v[46:47], off offset:2048 nt
	v_add_co_u32_e32 v54, vcc, s61, v62
	global_load_dwordx2 v[150:151], v[64:65], off offset:32
	global_load_dwordx2 v[152:153], v[64:65], off offset:64
	v_addc_co_u32_e32 v55, vcc, 0, v63, vcc
	global_load_dwordx2 v[154:155], v[64:65], off offset:96
	v_add_co_u32_e32 v58, vcc, s62, v62
	global_load_dwordx2 v[156:157], v[64:65], off offset:128
	s_nop 0
	global_load_dwordx4 v[50:53], v[50:51], off nt
	s_nop 0
	global_load_dwordx4 v[54:57], v[54:55], off offset:2048 nt
	s_nop 0
	global_load_dwordx2 v[158:159], v[64:65], off offset:160
	v_addc_co_u32_e32 v59, vcc, 0, v63, vcc
	v_add_co_u32_e32 v62, vcc, s63, v62
	global_load_dwordx4 v[58:61], v[58:59], off nt
	s_nop 0
	global_load_dwordx2 v[160:161], v[64:65], off offset:192
	global_load_dwordx2 v[162:163], v[64:65], off offset:224
	v_addc_co_u32_e32 v63, vcc, 0, v63, vcc
	global_load_dwordx4 v[62:65], v[62:63], off offset:2048 nt
	s_and_b32 s14, s19, 64
	s_add_i32 s14, s13, s14
	s_mulk_i32 s16, 0x2c00
	s_sub_i32 s14, s14, s16
	s_bitset1_b32 s14, 7
	s_lshl_b32 s4, s4, 7
	s_waitcnt vmcnt(13)
	v_pk_mul_f32 v[4:5], v[4:5], v[148:149] op_sel_hi:[1,0]
	v_pk_mul_f32 v[2:3], v[2:3], v[148:149] op_sel_hi:[1,0]
	v_pk_mul_f32 v[8:9], v[8:9], v[148:149] op_sel:[0,1]
	v_pk_mul_f32 v[6:7], v[6:7], v[148:149] op_sel:[0,1]
	s_waitcnt vmcnt(10)
	v_pk_mul_f32 v[12:13], v[12:13], v[150:151] op_sel_hi:[1,0]
	v_cvt_pk_bf16_f32 v2, v2, v6
	v_cvt_pk_bf16_f32 v3, v3, v7
	v_cvt_pk_bf16_f32 v4, v4, v8
	v_cvt_pk_bf16_f32 v5, v5, v9
	v_pk_mul_f32 v[10:11], v[10:11], v[150:151] op_sel_hi:[1,0]
	v_pk_mul_f32 v[16:17], v[16:17], v[150:151] op_sel:[0,1]
	v_pk_mul_f32 v[14:15], v[14:15], v[150:151] op_sel:[0,1]
	ds_write_b128 v94, v[2:5]
	v_cvt_pk_bf16_f32 v2, v10, v14
	v_cvt_pk_bf16_f32 v3, v11, v15
	v_cvt_pk_bf16_f32 v4, v12, v16
	v_cvt_pk_bf16_f32 v5, v13, v17
	s_waitcnt vmcnt(9)
	v_pk_mul_f32 v[20:21], v[20:21], v[152:153] op_sel_hi:[1,0]
	v_pk_mul_f32 v[18:19], v[18:19], v[152:153] op_sel_hi:[1,0]
	v_pk_mul_f32 v[24:25], v[24:25], v[152:153] op_sel:[0,1]
	v_pk_mul_f32 v[22:23], v[22:23], v[152:153] op_sel:[0,1]
	ds_write_b128 v94, v[2:5] offset:1088
	v_cvt_pk_bf16_f32 v2, v18, v22
	v_cvt_pk_bf16_f32 v3, v19, v23
	v_cvt_pk_bf16_f32 v4, v20, v24
	v_cvt_pk_bf16_f32 v5, v21, v25
	s_waitcnt vmcnt(8)
	v_pk_mul_f32 v[28:29], v[28:29], v[154:155] op_sel_hi:[1,0]
	v_pk_mul_f32 v[26:27], v[26:27], v[154:155] op_sel_hi:[1,0]
	v_pk_mul_f32 v[32:33], v[32:33], v[154:155] op_sel:[0,1]
	v_pk_mul_f32 v[30:31], v[30:31], v[154:155] op_sel:[0,1]
	ds_write_b128 v94, v[2:5] offset:2176
	v_cvt_pk_bf16_f32 v2, v26, v30
	v_cvt_pk_bf16_f32 v3, v27, v31
	v_cvt_pk_bf16_f32 v4, v28, v32
	v_cvt_pk_bf16_f32 v5, v29, v33
	s_waitcnt vmcnt(7)
	v_pk_mul_f32 v[36:37], v[36:37], v[156:157] op_sel_hi:[1,0]
	v_pk_mul_f32 v[34:35], v[34:35], v[156:157] op_sel_hi:[1,0]
	v_pk_mul_f32 v[40:41], v[40:41], v[156:157] op_sel:[0,1]
	v_pk_mul_f32 v[38:39], v[38:39], v[156:157] op_sel:[0,1]
	ds_write_b128 v94, v[2:5] offset:3264
	v_cvt_pk_bf16_f32 v2, v34, v38
	v_cvt_pk_bf16_f32 v3, v35, v39
	v_cvt_pk_bf16_f32 v4, v36, v40
	v_cvt_pk_bf16_f32 v5, v37, v41
	s_waitcnt vmcnt(4)
	v_pk_mul_f32 v[44:45], v[44:45], v[158:159] op_sel_hi:[1,0]
	v_pk_mul_f32 v[42:43], v[42:43], v[158:159] op_sel_hi:[1,0]
	v_pk_mul_f32 v[48:49], v[48:49], v[158:159] op_sel:[0,1]
	v_pk_mul_f32 v[46:47], v[46:47], v[158:159] op_sel:[0,1]
	ds_write_b128 v94, v[2:5] offset:4352
	v_cvt_pk_bf16_f32 v2, v42, v46
	v_cvt_pk_bf16_f32 v3, v43, v47
	v_cvt_pk_bf16_f32 v4, v44, v48
	v_cvt_pk_bf16_f32 v5, v45, v49
	s_waitcnt vmcnt(2)
	v_pk_mul_f32 v[52:53], v[52:53], v[160:161] op_sel_hi:[1,0]
	v_pk_mul_f32 v[50:51], v[50:51], v[160:161] op_sel_hi:[1,0]
	v_pk_mul_f32 v[56:57], v[56:57], v[160:161] op_sel:[0,1]
	v_pk_mul_f32 v[54:55], v[54:55], v[160:161] op_sel:[0,1]
	ds_write_b128 v94, v[2:5] offset:5440
	v_cvt_pk_bf16_f32 v2, v50, v54
	v_cvt_pk_bf16_f32 v3, v51, v55
	v_cvt_pk_bf16_f32 v4, v52, v56
	v_cvt_pk_bf16_f32 v5, v53, v57
	s_waitcnt vmcnt(1)
	v_pk_mul_f32 v[60:61], v[60:61], v[162:163] op_sel_hi:[1,0]
	v_pk_mul_f32 v[58:59], v[58:59], v[162:163] op_sel_hi:[1,0]
	s_waitcnt vmcnt(0)
	v_pk_mul_f32 v[64:65], v[64:65], v[162:163] op_sel:[0,1]
	v_pk_mul_f32 v[62:63], v[62:63], v[162:163] op_sel:[0,1]
	ds_write_b128 v94, v[2:5] offset:6528
	v_cvt_pk_bf16_f32 v2, v58, v62
	v_cvt_pk_bf16_f32 v3, v59, v63
	v_cvt_pk_bf16_f32 v4, v60, v64
	v_cvt_pk_bf16_f32 v5, v61, v65
	ds_write_b128 v94, v[2:5] offset:7616
	s_waitcnt lgkmcnt(0)
	v_add_u32_e32 v14, v95, v96
	ds_read_b128 v[2:5], v14
	ds_read_b128 v[6:9], v14 offset:272
	ds_read_b128 v[10:13], v14 offset:544
	ds_read_b128 v[14:17], v14 offset:816
	v_or_b32_e32 v24, s14, v97
	v_ashrrev_i32_e32 v25, 31, v24
	v_lshl_add_u64 v[22:23], v[72:73], 0, s[4:5]
	v_lshlrev_b64 v[26:27], 12, v[24:25]
	s_waitcnt lgkmcnt(3)
	v_mov_b32_e32 v18, v2
	s_waitcnt lgkmcnt(2)
	v_mov_b32_e32 v19, v6
	s_waitcnt lgkmcnt(1)
	v_mov_b32_e32 v20, v10
	s_waitcnt lgkmcnt(0)
	v_mov_b32_e32 v21, v14
	v_lshl_add_u64 v[26:27], v[22:23], 0, v[26:27]
	v_or_b32_e32 v2, 1, v24
	global_store_dwordx4 v[26:27], v[18:21], off
	v_mov_b32_e32 v14, v5
	s_nop 0
	v_mov_b32_e32 v18, v3
	v_ashrrev_i32_e32 v3, 31, v2
	v_lshlrev_b64 v[2:3], 12, v[2:3]
	v_mov_b32_e32 v19, v7
	v_mov_b32_e32 v20, v11
	v_mov_b32_e32 v21, v15
	v_lshl_add_u64 v[2:3], v[22:23], 0, v[2:3]
	global_store_dwordx4 v[2:3], v[18:21], off
	v_or_b32_e32 v2, 2, v24
	v_ashrrev_i32_e32 v3, 31, v2
	v_lshlrev_b64 v[2:3], 12, v[2:3]
	v_mov_b32_e32 v18, v4
	v_mov_b32_e32 v19, v8
	v_mov_b32_e32 v20, v12
	v_mov_b32_e32 v21, v16
	v_lshl_add_u64 v[2:3], v[22:23], 0, v[2:3]
	global_store_dwordx4 v[2:3], v[18:21], off
	v_or_b32_e32 v2, 3, v24
	v_ashrrev_i32_e32 v3, 31, v2
	v_lshlrev_b64 v[2:3], 12, v[2:3]
	v_mov_b32_e32 v15, v9
	v_mov_b32_e32 v16, v13
	v_lshl_add_u64 v[2:3], v[22:23], 0, v[2:3]
	global_store_dwordx4 v[2:3], v[14:17], off
	v_or_b32_e32 v24, s14, v99
	v_ashrrev_i32_e32 v25, 31, v24
	v_add_u32_e32 v14, v98, v96
	ds_read_b128 v[2:5], v14
	ds_read_b128 v[6:9], v14 offset:272
	ds_read_b128 v[10:13], v14 offset:544
	ds_read_b128 v[14:17], v14 offset:816
	v_lshlrev_b64 v[26:27], 12, v[24:25]
	s_waitcnt lgkmcnt(3)
	v_mov_b32_e32 v18, v2
	s_waitcnt lgkmcnt(2)
	v_mov_b32_e32 v19, v6
	s_waitcnt lgkmcnt(1)
	v_mov_b32_e32 v20, v10
	s_waitcnt lgkmcnt(0)
	v_mov_b32_e32 v21, v14
	v_lshl_add_u64 v[26:27], v[22:23], 0, v[26:27]
	v_or_b32_e32 v2, 1, v24
	global_store_dwordx4 v[26:27], v[18:21], off
	v_mov_b32_e32 v14, v5
	s_mov_b64 s[14:15], 0
	v_mov_b32_e32 v18, v3
	v_ashrrev_i32_e32 v3, 31, v2
	v_lshlrev_b64 v[2:3], 12, v[2:3]
	v_mov_b32_e32 v19, v7
	v_mov_b32_e32 v20, v11
	v_mov_b32_e32 v21, v15
	v_lshl_add_u64 v[2:3], v[22:23], 0, v[2:3]
	global_store_dwordx4 v[2:3], v[18:21], off
	v_or_b32_e32 v2, 2, v24
	v_ashrrev_i32_e32 v3, 31, v2
	v_lshlrev_b64 v[2:3], 12, v[2:3]
	v_mov_b32_e32 v18, v4
	v_mov_b32_e32 v19, v8
	v_mov_b32_e32 v20, v12
	v_mov_b32_e32 v21, v16
	v_lshl_add_u64 v[2:3], v[22:23], 0, v[2:3]
	global_store_dwordx4 v[2:3], v[18:21], off
	v_or_b32_e32 v2, 3, v24
	v_ashrrev_i32_e32 v3, 31, v2
	v_lshlrev_b64 v[2:3], 12, v[2:3]
	v_mov_b32_e32 v15, v9
	v_mov_b32_e32 v16, v13
	v_lshl_add_u64 v[2:3], v[22:23], 0, v[2:3]
	global_store_dwordx4 v[2:3], v[14:17], off
	s_waitcnt lgkmcnt(0)
.LBB0_21:
	s_andn2_b64 vcc, exec, s[14:15]
	s_cbranch_vccnz .LBB0_23
	s_and_b32 s4, 0xffff, s23
	s_mul_hi_u32 s53, s4, 0x2e8ba2f
	s_mul_i32 s4, s11, 0xba2f
	s_mov_b64 s[14:15], s[0:1]
	s_add_i32 s4, s4, 0x8000500
	s_load_dwordx2 s[54:55], s[14:15], 0xb0
	s_lshr_b32 s4, s4, 22
	s_mov_b64 s[14:15], s[0:1]
	s_lshl_b32 s56, s4, 6
	s_mul_i32 vcc_lo, s53, 0xffffea00
	v_or_b32_e32 v2, s56, v67
	s_load_dwordx2 s[16:17], s[14:15], 0x18
	s_add_i32 s14, s21, vcc_lo
	v_mul_u32_u24_e32 v2, 0x1600, v2
	s_add_i32 s14, s14, 0x2c000
	v_lshlrev_b32_e32 v70, 2, v2
	s_waitcnt lgkmcnt(0)
	v_lshl_add_u64 v[2:3], s[54:55], 0, v[70:71]
	s_ashr_i32 s15, s14, 31
	v_lshl_add_u64 v[2:3], s[14:15], 2, v[2:3]
	v_lshlrev_b32_e32 v70, 2, v68
	s_mov_b32 vcc_hi, 0x2c00000
	v_lshl_add_u64 v[62:63], v[2:3], 0, v[70:71]
	v_add_co_u32_e32 v2, vcc, vcc_hi, v62
	s_mov_b32 s15, 0x2c05000
	s_nop 0
	v_addc_co_u32_e32 v3, vcc, 0, v63, vcc
	v_add_co_u32_e32 v6, vcc, s15, v62
	s_mov_b32 s15, 0x2c2c000
	s_nop 0
	v_addc_co_u32_e32 v7, vcc, 0, v63, vcc
	v_add_co_u32_e32 v10, vcc, s15, v62
	s_mov_b32 s15, 0x2c31000
	s_nop 0
	v_addc_co_u32_e32 v11, vcc, 0, v63, vcc
	v_add_co_u32_e32 v14, vcc, s15, v62
	s_mov_b32 s15, 0x2c58000
	s_nop 0
	v_addc_co_u32_e32 v15, vcc, 0, v63, vcc
	v_add_co_u32_e32 v18, vcc, s15, v62
	s_mov_b32 s15, 0x2c5d000
	s_nop 0
	v_addc_co_u32_e32 v19, vcc, 0, v63, vcc
	v_add_co_u32_e32 v22, vcc, s15, v62
	s_mov_b32 s15, 0x2c84000
	s_nop 0
	v_addc_co_u32_e32 v23, vcc, 0, v63, vcc
	v_add_co_u32_e32 v26, vcc, s15, v62
	s_mov_b32 s15, 0x2c89000
	s_nop 0
	v_addc_co_u32_e32 v27, vcc, 0, v63, vcc
	v_add_co_u32_e32 v30, vcc, s15, v62
	s_mov_b32 s15, 0x2cb0000
	s_nop 0
	v_addc_co_u32_e32 v31, vcc, 0, v63, vcc
	v_add_co_u32_e32 v34, vcc, s15, v62
	v_or_b32_e32 v44, s56, v93
	s_nop 0
	v_addc_co_u32_e32 v35, vcc, 0, v63, vcc
	v_add_co_u32_e32 v38, vcc, s57, v62
	v_lshlrev_b32_e32 v70, 2, v44
	s_nop 0
	v_addc_co_u32_e32 v39, vcc, 0, v63, vcc
	v_add_co_u32_e32 v42, vcc, s58, v62
	v_lshl_add_u64 v[50:51], s[16:17], 0, v[70:71]
	s_nop 0
	v_addc_co_u32_e32 v43, vcc, 0, v63, vcc
	v_add_co_u32_e32 v46, vcc, s59, v62
	v_lshl_add_u64 v[64:65], v[50:51], 0, s[6:7]
	s_nop 0
	v_addc_co_u32_e32 v47, vcc, 0, v63, vcc
	v_add_co_u32_e32 v44, vcc, s64, v50
	global_load_dwordx4 v[2:5], v[2:3], off nt
	s_nop 0
	global_load_dwordx4 v[6:9], v[6:7], off offset:2048 nt
	v_addc_co_u32_e32 v45, vcc, 0, v51, vcc
	v_add_co_u32_e32 v50, vcc, s60, v62
	global_load_dwordx4 v[10:13], v[10:11], off nt
	s_nop 0
	global_load_dwordx4 v[14:17], v[14:15], off offset:2048 nt
	v_addc_co_u32_e32 v51, vcc, 0, v63, vcc
	global_load_dwordx4 v[18:21], v[18:19], off nt
	s_nop 0
	global_load_dwordx4 v[22:25], v[22:23], off offset:2048 nt
	s_nop 0
	global_load_dwordx4 v[26:29], v[26:27], off nt
	s_nop 0
	global_load_dwordx4 v[30:33], v[30:31], off offset:2048 nt
	s_nop 0
	global_load_dwordx4 v[34:37], v[34:35], off nt
	s_nop 0
	global_load_dwordx4 v[38:41], v[38:39], off offset:2048 nt
	s_nop 0
	global_load_dwordx2 v[148:149], v[44:45], off
	s_nop 0
	global_load_dwordx4 v[42:45], v[42:43], off nt
	s_nop 0
	global_load_dwordx4 v[46:49], v[46:47], off offset:2048 nt
	v_add_co_u32_e32 v54, vcc, s61, v62
	global_load_dwordx2 v[150:151], v[64:65], off offset:32
	global_load_dwordx2 v[152:153], v[64:65], off offset:64
	v_addc_co_u32_e32 v55, vcc, 0, v63, vcc
	global_load_dwordx2 v[154:155], v[64:65], off offset:96
	v_add_co_u32_e32 v58, vcc, s62, v62
	global_load_dwordx2 v[156:157], v[64:65], off offset:128
	s_nop 0
	global_load_dwordx4 v[50:53], v[50:51], off nt
	s_nop 0
	global_load_dwordx4 v[54:57], v[54:55], off offset:2048 nt
	s_nop 0
	global_load_dwordx2 v[158:159], v[64:65], off offset:160
	v_addc_co_u32_e32 v59, vcc, 0, v63, vcc
	v_add_co_u32_e32 v62, vcc, s63, v62
	global_load_dwordx4 v[58:61], v[58:59], off nt
	s_nop 0
	global_load_dwordx2 v[160:161], v[64:65], off offset:192
	global_load_dwordx2 v[162:163], v[64:65], off offset:224
	v_addc_co_u32_e32 v63, vcc, 0, v63, vcc
	global_load_dwordx4 v[62:65], v[62:63], off offset:2048 nt
	s_mulk_i32 s53, 0x2c00
	s_sub_i32 s15, s22, s53
	s_and_b32 s15, s15, 0xffffff00
	s_and_b32 s14, s14, 64
	s_or_b32 s14, s14, s15
	s_lshl_b32 s4, s4, 7
	s_mov_b32 s56, 0x2c00000
	s_waitcnt vmcnt(13)
	v_pk_mul_f32 v[4:5], v[4:5], v[148:149] op_sel_hi:[1,0]
	v_pk_mul_f32 v[2:3], v[2:3], v[148:149] op_sel_hi:[1,0]
	v_pk_mul_f32 v[8:9], v[8:9], v[148:149] op_sel:[0,1]
	v_pk_mul_f32 v[6:7], v[6:7], v[148:149] op_sel:[0,1]
	s_waitcnt vmcnt(10)
	v_pk_mul_f32 v[12:13], v[12:13], v[150:151] op_sel_hi:[1,0]
	v_cvt_pk_bf16_f32 v2, v2, v6
	v_cvt_pk_bf16_f32 v3, v3, v7
	v_cvt_pk_bf16_f32 v4, v4, v8
	v_cvt_pk_bf16_f32 v5, v5, v9
	v_pk_mul_f32 v[10:11], v[10:11], v[150:151] op_sel_hi:[1,0]
	v_pk_mul_f32 v[16:17], v[16:17], v[150:151] op_sel:[0,1]
	v_pk_mul_f32 v[14:15], v[14:15], v[150:151] op_sel:[0,1]
	ds_write_b128 v94, v[2:5]
	v_cvt_pk_bf16_f32 v2, v10, v14
	v_cvt_pk_bf16_f32 v3, v11, v15
	v_cvt_pk_bf16_f32 v4, v12, v16
	v_cvt_pk_bf16_f32 v5, v13, v17
	s_waitcnt vmcnt(9)
	v_pk_mul_f32 v[20:21], v[20:21], v[152:153] op_sel_hi:[1,0]
	v_pk_mul_f32 v[18:19], v[18:19], v[152:153] op_sel_hi:[1,0]
	v_pk_mul_f32 v[24:25], v[24:25], v[152:153] op_sel:[0,1]
	v_pk_mul_f32 v[22:23], v[22:23], v[152:153] op_sel:[0,1]
	ds_write_b128 v94, v[2:5] offset:1088
	v_cvt_pk_bf16_f32 v2, v18, v22
	v_cvt_pk_bf16_f32 v3, v19, v23
	v_cvt_pk_bf16_f32 v4, v20, v24
	v_cvt_pk_bf16_f32 v5, v21, v25
	s_waitcnt vmcnt(8)
	v_pk_mul_f32 v[28:29], v[28:29], v[154:155] op_sel_hi:[1,0]
	v_pk_mul_f32 v[26:27], v[26:27], v[154:155] op_sel_hi:[1,0]
	v_pk_mul_f32 v[32:33], v[32:33], v[154:155] op_sel:[0,1]
	v_pk_mul_f32 v[30:31], v[30:31], v[154:155] op_sel:[0,1]
	ds_write_b128 v94, v[2:5] offset:2176
	v_cvt_pk_bf16_f32 v2, v26, v30
	v_cvt_pk_bf16_f32 v3, v27, v31
	v_cvt_pk_bf16_f32 v4, v28, v32
	v_cvt_pk_bf16_f32 v5, v29, v33
	s_waitcnt vmcnt(7)
	v_pk_mul_f32 v[36:37], v[36:37], v[156:157] op_sel_hi:[1,0]
	v_pk_mul_f32 v[34:35], v[34:35], v[156:157] op_sel_hi:[1,0]
	v_pk_mul_f32 v[40:41], v[40:41], v[156:157] op_sel:[0,1]
	v_pk_mul_f32 v[38:39], v[38:39], v[156:157] op_sel:[0,1]
	ds_write_b128 v94, v[2:5] offset:3264
	v_cvt_pk_bf16_f32 v2, v34, v38
	v_cvt_pk_bf16_f32 v3, v35, v39
	v_cvt_pk_bf16_f32 v4, v36, v40
	v_cvt_pk_bf16_f32 v5, v37, v41
	s_waitcnt vmcnt(4)
	v_pk_mul_f32 v[44:45], v[44:45], v[158:159] op_sel_hi:[1,0]
	v_pk_mul_f32 v[42:43], v[42:43], v[158:159] op_sel_hi:[1,0]
	v_pk_mul_f32 v[48:49], v[48:49], v[158:159] op_sel:[0,1]
	v_pk_mul_f32 v[46:47], v[46:47], v[158:159] op_sel:[0,1]
	ds_write_b128 v94, v[2:5] offset:4352
	v_cvt_pk_bf16_f32 v2, v42, v46
	v_cvt_pk_bf16_f32 v3, v43, v47
	v_cvt_pk_bf16_f32 v4, v44, v48
	v_cvt_pk_bf16_f32 v5, v45, v49
	s_waitcnt vmcnt(2)
	v_pk_mul_f32 v[52:53], v[52:53], v[160:161] op_sel_hi:[1,0]
	v_pk_mul_f32 v[50:51], v[50:51], v[160:161] op_sel_hi:[1,0]
	v_pk_mul_f32 v[56:57], v[56:57], v[160:161] op_sel:[0,1]
	v_pk_mul_f32 v[54:55], v[54:55], v[160:161] op_sel:[0,1]
	ds_write_b128 v94, v[2:5] offset:5440
	v_cvt_pk_bf16_f32 v2, v50, v54
	v_cvt_pk_bf16_f32 v3, v51, v55
	v_cvt_pk_bf16_f32 v4, v52, v56
	v_cvt_pk_bf16_f32 v5, v53, v57
	s_waitcnt vmcnt(1)
	v_pk_mul_f32 v[60:61], v[60:61], v[162:163] op_sel_hi:[1,0]
	v_pk_mul_f32 v[58:59], v[58:59], v[162:163] op_sel_hi:[1,0]
	s_waitcnt vmcnt(0)
	v_pk_mul_f32 v[64:65], v[64:65], v[162:163] op_sel:[0,1]
	v_pk_mul_f32 v[62:63], v[62:63], v[162:163] op_sel:[0,1]
	ds_write_b128 v94, v[2:5] offset:6528
	v_cvt_pk_bf16_f32 v2, v58, v62
	v_cvt_pk_bf16_f32 v3, v59, v63
	v_cvt_pk_bf16_f32 v4, v60, v64
	v_cvt_pk_bf16_f32 v5, v61, v65
	ds_write_b128 v94, v[2:5] offset:7616
	s_waitcnt lgkmcnt(0)
	v_add_u32_e32 v14, v95, v96
	ds_read_b128 v[2:5], v14
	ds_read_b128 v[6:9], v14 offset:272
	ds_read_b128 v[10:13], v14 offset:544
	ds_read_b128 v[14:17], v14 offset:816
	v_or_b32_e32 v24, s14, v97
	v_ashrrev_i32_e32 v25, 31, v24
	v_lshl_add_u64 v[22:23], v[72:73], 0, s[4:5]
	v_lshlrev_b64 v[26:27], 12, v[24:25]
	s_waitcnt lgkmcnt(3)
	v_mov_b32_e32 v18, v2
	s_waitcnt lgkmcnt(2)
	v_mov_b32_e32 v19, v6
	s_waitcnt lgkmcnt(1)
	v_mov_b32_e32 v20, v10
	s_waitcnt lgkmcnt(0)
	v_mov_b32_e32 v21, v14
	v_lshl_add_u64 v[26:27], v[22:23], 0, v[26:27]
	v_or_b32_e32 v2, 1, v24
	global_store_dwordx4 v[26:27], v[18:21], off
	v_mov_b32_e32 v14, v5
	s_nop 0
	v_mov_b32_e32 v18, v3
	v_ashrrev_i32_e32 v3, 31, v2
	v_lshlrev_b64 v[2:3], 12, v[2:3]
	v_mov_b32_e32 v19, v7
	v_mov_b32_e32 v20, v11
	v_mov_b32_e32 v21, v15
	v_lshl_add_u64 v[2:3], v[22:23], 0, v[2:3]
	global_store_dwordx4 v[2:3], v[18:21], off
	v_or_b32_e32 v2, 2, v24
	v_ashrrev_i32_e32 v3, 31, v2
	v_lshlrev_b64 v[2:3], 12, v[2:3]
	v_mov_b32_e32 v18, v4
	v_mov_b32_e32 v19, v8
	v_mov_b32_e32 v20, v12
	v_mov_b32_e32 v21, v16
	v_lshl_add_u64 v[2:3], v[22:23], 0, v[2:3]
	global_store_dwordx4 v[2:3], v[18:21], off
	v_or_b32_e32 v2, 3, v24
	v_ashrrev_i32_e32 v3, 31, v2
	v_lshlrev_b64 v[2:3], 12, v[2:3]
	v_mov_b32_e32 v15, v9
	v_mov_b32_e32 v16, v13
	v_lshl_add_u64 v[2:3], v[22:23], 0, v[2:3]
	global_store_dwordx4 v[2:3], v[14:17], off
	v_or_b32_e32 v24, s14, v99
	v_ashrrev_i32_e32 v25, 31, v24
	v_add_u32_e32 v14, v98, v96
	ds_read_b128 v[2:5], v14
	ds_read_b128 v[6:9], v14 offset:272
	ds_read_b128 v[10:13], v14 offset:544
	ds_read_b128 v[14:17], v14 offset:816
	v_lshlrev_b64 v[26:27], 12, v[24:25]
	s_waitcnt lgkmcnt(3)
	v_mov_b32_e32 v18, v2
	s_waitcnt lgkmcnt(2)
	v_mov_b32_e32 v19, v6
	s_waitcnt lgkmcnt(1)
	v_mov_b32_e32 v20, v10
	s_waitcnt lgkmcnt(0)
	v_mov_b32_e32 v21, v14
	v_lshl_add_u64 v[26:27], v[22:23], 0, v[26:27]
	v_or_b32_e32 v2, 1, v24
	global_store_dwordx4 v[26:27], v[18:21], off
	v_mov_b32_e32 v14, v5
	s_nop 0
	v_mov_b32_e32 v18, v3
	v_ashrrev_i32_e32 v3, 31, v2
	v_lshlrev_b64 v[2:3], 12, v[2:3]
	v_mov_b32_e32 v19, v7
	v_mov_b32_e32 v20, v11
	v_mov_b32_e32 v21, v15
	v_lshl_add_u64 v[2:3], v[22:23], 0, v[2:3]
	global_store_dwordx4 v[2:3], v[18:21], off
	v_or_b32_e32 v2, 2, v24
	v_ashrrev_i32_e32 v3, 31, v2
	v_lshlrev_b64 v[2:3], 12, v[2:3]
	v_mov_b32_e32 v18, v4
	v_mov_b32_e32 v19, v8
	v_mov_b32_e32 v20, v12
	v_mov_b32_e32 v21, v16
	v_lshl_add_u64 v[2:3], v[22:23], 0, v[2:3]
	global_store_dwordx4 v[2:3], v[18:21], off
	v_or_b32_e32 v2, 3, v24
	v_ashrrev_i32_e32 v3, 31, v2
	v_lshlrev_b64 v[2:3], 12, v[2:3]
	v_mov_b32_e32 v15, v9
	v_mov_b32_e32 v16, v13
	v_lshl_add_u64 v[2:3], v[22:23], 0, v[2:3]
	global_store_dwordx4 v[2:3], v[14:17], off
	s_waitcnt lgkmcnt(0)

.LBB0_24:
	s_andn2_b64 vcc, exec, s[14:15]
	s_cbranch_vccnz .LBB0_26
	s_mov_b64 s[14:15], s[0:1]
	s_load_dwordx2 s[16:17], s[14:15], 0xa8
	s_and_b32 s4, s24, 0x7fc0
	s_add_i32 s14, s4, 0xffff9400
	s_add_i32 s15, s21, 0x114000
	v_or_b32_e32 v2, s14, v67
	s_and_b32 s4, s15, 0x7c0
	v_lshlrev_b32_e32 v70, 12, v2
	s_waitcnt lgkmcnt(0)
	v_lshl_add_u64 v[2:3], v[70:71], 2, s[16:17]
	s_lshl_b32 s4, s4, 2
	v_lshl_add_u64 v[2:3], v[2:3], 0, s[4:5]
	v_lshlrev_b32_e32 v70, 2, v68
	v_lshl_add_u64 v[58:59], v[2:3], 0, v[70:71]
	v_add_co_u32_e32 v6, vcc, s66, v58
	s_mov_b32 s4, 0xc4000
	s_nop 0
	v_addc_co_u32_e32 v7, vcc, 0, v59, vcc
	v_add_co_u32_e32 v10, vcc, s67, v58
	global_load_dwordx4 v[2:5], v[58:59], off nt
	s_nop 0
	global_load_dwordx4 v[6:9], v[6:7], off nt
	v_addc_co_u32_e32 v11, vcc, 0, v59, vcc
	v_add_co_u32_e32 v14, vcc, s70, v58
	s_and_b32 s15, s15, 64
	s_nop 0
	v_addc_co_u32_e32 v15, vcc, 0, v59, vcc
	v_add_co_u32_e32 v18, vcc, s71, v58
	global_load_dwordx4 v[10:13], v[10:11], off nt
	s_nop 0
	global_load_dwordx4 v[14:17], v[14:15], off nt
	v_addc_co_u32_e32 v19, vcc, 0, v59, vcc
	v_add_co_u32_e32 v22, vcc, s72, v58
	s_nop 1
	v_addc_co_u32_e32 v23, vcc, 0, v59, vcc
	v_add_co_u32_e32 v26, vcc, s73, v58
	global_load_dwordx4 v[18:21], v[18:19], off nt
	s_nop 0
	global_load_dwordx4 v[22:25], v[22:23], off nt
	v_addc_co_u32_e32 v27, vcc, 0, v59, vcc
	v_add_co_u32_e32 v30, vcc, s74, v58
	s_nop 1
	v_addc_co_u32_e32 v31, vcc, 0, v59, vcc
	v_add_co_u32_e32 v34, vcc, s75, v58
	global_load_dwordx4 v[26:29], v[26:27], off nt
	s_nop 0
	global_load_dwordx4 v[30:33], v[30:31], off nt
	v_addc_co_u32_e32 v35, vcc, 0, v59, vcc
	v_add_co_u32_e32 v38, vcc, s76, v58
	s_nop 1
	v_addc_co_u32_e32 v39, vcc, 0, v59, vcc
	v_add_co_u32_e32 v42, vcc, s77, v58
	global_load_dwordx4 v[34:37], v[34:35], off nt
	s_nop 0
	global_load_dwordx4 v[38:41], v[38:39], off nt
	v_addc_co_u32_e32 v43, vcc, 0, v59, vcc
	v_add_co_u32_e32 v46, vcc, s78, v58
	s_nop 1
	v_addc_co_u32_e32 v47, vcc, 0, v59, vcc
	v_add_co_u32_e32 v50, vcc, s79, v58
	global_load_dwordx4 v[42:45], v[42:43], off nt
	s_nop 0
	global_load_dwordx4 v[46:49], v[46:47], off nt
	v_addc_co_u32_e32 v51, vcc, 0, v59, vcc
	v_add_co_u32_e32 v54, vcc, s4, v58
	s_mov_b32 s4, 0xe0000
	s_nop 0
	v_addc_co_u32_e32 v55, vcc, 0, v59, vcc
	v_add_co_u32_e32 v60, vcc, s4, v58
	s_mov_b32 s4, 0xe4000
	s_nop 0
	v_addc_co_u32_e32 v61, vcc, 0, v59, vcc
	v_add_co_u32_e32 v62, vcc, s4, v58
	global_load_dwordx4 v[50:53], v[50:51], off nt
	s_nop 0
	global_load_dwordx4 v[54:57], v[54:55], off nt
	v_addc_co_u32_e32 v63, vcc, 0, v59, vcc
	global_load_dwordx4 v[58:61], v[60:61], off nt
	s_nop 0
	global_load_dwordx4 v[62:65], v[62:63], off nt
	s_and_b32 s4, s26, 0xf00
	s_waitcnt vmcnt(14)
	v_cvt_pk_bf16_f32 v2, v2, v6
	v_cvt_pk_bf16_f32 v3, v3, v7
	v_cvt_pk_bf16_f32 v4, v4, v8
	v_cvt_pk_bf16_f32 v5, v5, v9
	ds_write_b128 v94, v[2:5]
	s_waitcnt vmcnt(12)
	v_cvt_pk_bf16_f32 v2, v10, v14
	v_cvt_pk_bf16_f32 v3, v11, v15
	v_cvt_pk_bf16_f32 v4, v12, v16
	v_cvt_pk_bf16_f32 v5, v13, v17
	ds_write_b128 v94, v[2:5] offset:1088
	s_waitcnt vmcnt(10)
	v_cvt_pk_bf16_f32 v2, v18, v22
	v_cvt_pk_bf16_f32 v3, v19, v23
	v_cvt_pk_bf16_f32 v4, v20, v24
	v_cvt_pk_bf16_f32 v5, v21, v25
	ds_write_b128 v94, v[2:5] offset:2176
	s_waitcnt vmcnt(8)
	v_cvt_pk_bf16_f32 v2, v26, v30
	v_cvt_pk_bf16_f32 v3, v27, v31
	v_cvt_pk_bf16_f32 v4, v28, v32
	v_cvt_pk_bf16_f32 v5, v29, v33
	ds_write_b128 v94, v[2:5] offset:3264
	s_waitcnt vmcnt(6)
	v_cvt_pk_bf16_f32 v2, v34, v38
	v_cvt_pk_bf16_f32 v3, v35, v39
	v_cvt_pk_bf16_f32 v4, v36, v40
	v_cvt_pk_bf16_f32 v5, v37, v41
	ds_write_b128 v94, v[2:5] offset:4352
	s_waitcnt vmcnt(4)
	v_cvt_pk_bf16_f32 v2, v42, v46
	v_cvt_pk_bf16_f32 v3, v43, v47
	v_cvt_pk_bf16_f32 v4, v44, v48
	v_cvt_pk_bf16_f32 v5, v45, v49
	ds_write_b128 v94, v[2:5] offset:5440
	s_waitcnt vmcnt(2)
	v_cvt_pk_bf16_f32 v2, v50, v54
	v_cvt_pk_bf16_f32 v3, v51, v55
	v_cvt_pk_bf16_f32 v4, v52, v56
	v_cvt_pk_bf16_f32 v5, v53, v57
	ds_write_b128 v94, v[2:5] offset:6528
	s_waitcnt vmcnt(0)
	v_cvt_pk_bf16_f32 v2, v58, v62
	v_cvt_pk_bf16_f32 v3, v59, v63
	v_cvt_pk_bf16_f32 v4, v60, v64
	v_cvt_pk_bf16_f32 v5, v61, v65
	ds_write_b128 v94, v[2:5] offset:7616
	s_waitcnt lgkmcnt(0)
	v_add_u32_e32 v14, v95, v96
	ds_read_b128 v[2:5], v14
	ds_read_b128 v[6:9], v14 offset:272
	ds_read_b128 v[10:13], v14 offset:544
	ds_read_b128 v[14:17], v14 offset:816
	s_or_b32 s4, s15, s4
	s_mov_b32 s15, s5
	v_or_b32_e32 v24, s4, v97
	v_lshl_add_u64 v[22:23], s[14:15], 1, v[74:75]
	v_lshlrev_b32_e32 v70, 12, v24
	v_lshl_add_u64 v[24:25], v[22:23], 0, v[70:71]
	s_waitcnt lgkmcnt(3)
	v_mov_b32_e32 v18, v2
	s_waitcnt lgkmcnt(2)
	v_mov_b32_e32 v19, v6
	s_waitcnt lgkmcnt(1)
	v_mov_b32_e32 v20, v10
	s_waitcnt lgkmcnt(0)
	v_mov_b32_e32 v21, v14
	v_add_co_u32_e32 v2, vcc, s64, v24
	global_store_dwordx4 v[24:25], v[18:21], off
	s_movk_i32 s14, 0x3000
	v_mov_b32_e32 v14, v5
	v_mov_b32_e32 v18, v3
	v_mov_b32_e32 v19, v7
	v_mov_b32_e32 v20, v11
	v_mov_b32_e32 v21, v15
	v_addc_co_u32_e32 v3, vcc, 0, v25, vcc
	global_store_dwordx4 v[2:3], v[18:21], off offset:-4096
	v_mov_b32_e32 v15, v9
	s_nop 0
	v_mov_b32_e32 v18, v4
	v_mov_b32_e32 v19, v8
	v_mov_b32_e32 v20, v12
	v_mov_b32_e32 v21, v16
	global_store_dwordx4 v[2:3], v[18:21], off
	v_add_co_u32_e32 v2, vcc, s14, v24
	v_mov_b32_e32 v16, v13
	s_nop 0
	v_addc_co_u32_e32 v3, vcc, 0, v25, vcc
	global_store_dwordx4 v[2:3], v[14:17], off
	v_or_b32_e32 v24, s4, v99
	v_lshlrev_b32_e32 v70, 12, v24
	v_add_u32_e32 v14, v98, v96
	ds_read_b128 v[2:5], v14
	ds_read_b128 v[6:9], v14 offset:272
	ds_read_b128 v[10:13], v14 offset:544
	ds_read_b128 v[14:17], v14 offset:816
	v_lshl_add_u64 v[22:23], v[22:23], 0, v[70:71]
	s_waitcnt lgkmcnt(3)
	v_mov_b32_e32 v18, v2
	s_waitcnt lgkmcnt(2)
	v_mov_b32_e32 v19, v6
	s_waitcnt lgkmcnt(1)
	v_mov_b32_e32 v20, v10
	s_waitcnt lgkmcnt(0)
	v_mov_b32_e32 v21, v14
	v_add_co_u32_e32 v2, vcc, 0x1000, v22
	global_store_dwordx4 v[22:23], v[18:21], off
	v_mov_b32_e32 v14, v5
	s_nop 0
	v_mov_b32_e32 v18, v3
	v_mov_b32_e32 v19, v7
	v_mov_b32_e32 v20, v11
	v_mov_b32_e32 v21, v15
	v_addc_co_u32_e32 v3, vcc, 0, v23, vcc
	global_store_dwordx4 v[2:3], v[18:21], off
	v_add_co_u32_e32 v2, vcc, 0x2000, v22
	s_nop 0
	v_mov_b32_e32 v18, v4
	v_mov_b32_e32 v19, v8
	v_mov_b32_e32 v20, v12
	v_mov_b32_e32 v21, v16
	v_addc_co_u32_e32 v3, vcc, 0, v23, vcc
	global_store_dwordx4 v[2:3], v[18:21], off
	v_add_co_u32_e32 v2, vcc, 0x3000, v22
	v_mov_b32_e32 v15, v9
	v_mov_b32_e32 v16, v13
	v_addc_co_u32_e32 v3, vcc, 0, v23, vcc
	global_store_dwordx4 v[2:3], v[14:17], off
	s_waitcnt lgkmcnt(0)

.LBB0_27:
	s_andn2_b64 vcc, exec, s[14:15]
	s_cbranch_vccnz .LBB0_29
	s_mov_b64 s[14:15], s[0:1]
	s_lshl_b32 s4, s11, 1
	s_load_dwordx2 s[16:17], s[14:15], 0xd0
	s_addk_i32 s4, 0x1f00
	s_lshl_b32 s14, s27, 6
	s_andn2_b32 s4, s4, 63
	s_and_b32 s14, s14, 0xfffff800
	s_sub_i32 s14, s21, s14
	v_or_b32_e32 v2, s4, v67
	s_add_i32 s54, s14, 0x3e000
	v_lshlrev_b32_e32 v70, 11, v2
	s_waitcnt lgkmcnt(0)
	v_lshl_add_u64 v[2:3], v[70:71], 2, s[16:17]
	s_ashr_i32 s55, s54, 31
	v_lshl_add_u64 v[2:3], s[54:55], 2, v[2:3]
	v_lshlrev_b32_e32 v70, 2, v68
	v_lshl_add_u64 v[58:59], v[2:3], 0, v[70:71]
	s_mov_b32 s15, 0x200000
	v_add_co_u32_e32 v2, vcc, s15, v58
	s_mov_b32 s15, 0x202000
	s_nop 0
	v_addc_co_u32_e32 v3, vcc, 0, v59, vcc
	v_add_co_u32_e32 v6, vcc, s15, v58
	s_mov_b32 s15, 0x210000
	s_nop 0
	v_addc_co_u32_e32 v7, vcc, 0, v59, vcc
	v_add_co_u32_e32 v10, vcc, s15, v58
	s_mov_b32 s15, 0x212000
	s_nop 0
	v_addc_co_u32_e32 v11, vcc, 0, v59, vcc
	v_add_co_u32_e32 v14, vcc, s15, v58
	s_mov_b32 s15, 0x220000
	s_nop 0
	v_addc_co_u32_e32 v15, vcc, 0, v59, vcc
	v_add_co_u32_e32 v18, vcc, s15, v58
	s_mov_b32 s15, 0x222000
	s_nop 0
	v_addc_co_u32_e32 v19, vcc, 0, v59, vcc
	v_add_co_u32_e32 v22, vcc, s15, v58
	s_mov_b32 s15, 0x230000
	s_nop 0
	v_addc_co_u32_e32 v23, vcc, 0, v59, vcc
	v_add_co_u32_e32 v26, vcc, s15, v58
	s_mov_b32 s15, 0x232000
	s_nop 0
	v_addc_co_u32_e32 v27, vcc, 0, v59, vcc
	v_add_co_u32_e32 v30, vcc, s15, v58
	s_mov_b32 s15, 0x240000
	s_nop 0
	v_addc_co_u32_e32 v31, vcc, 0, v59, vcc
	v_add_co_u32_e32 v34, vcc, s15, v58
	s_mov_b32 s15, 0x242000
	s_nop 0
	v_addc_co_u32_e32 v35, vcc, 0, v59, vcc
	v_add_co_u32_e32 v38, vcc, s15, v58
	s_mov_b32 s15, 0x250000
	s_nop 0
	v_addc_co_u32_e32 v39, vcc, 0, v59, vcc
	v_add_co_u32_e32 v42, vcc, s15, v58
	s_mov_b32 s15, 0x252000
	s_nop 0
	v_addc_co_u32_e32 v43, vcc, 0, v59, vcc
	v_add_co_u32_e32 v46, vcc, s15, v58
	s_mov_b32 s15, 0x260000
	s_nop 0
	v_addc_co_u32_e32 v47, vcc, 0, v59, vcc
	v_add_co_u32_e32 v50, vcc, s15, v58
	global_load_dwordx4 v[2:5], v[2:3], off nt
	s_nop 0
	global_load_dwordx4 v[6:9], v[6:7], off nt
	v_addc_co_u32_e32 v51, vcc, 0, v59, vcc
	s_mov_b32 s15, 0x262000
	global_load_dwordx4 v[10:13], v[10:11], off nt
	s_nop 0
	global_load_dwordx4 v[14:17], v[14:15], off nt
	v_add_co_u32_e32 v54, vcc, s15, v58
	global_load_dwordx4 v[18:21], v[18:19], off nt
	s_nop 0
	global_load_dwordx4 v[22:25], v[22:23], off nt
	v_addc_co_u32_e32 v55, vcc, 0, v59, vcc
	s_mov_b32 s15, 0x270000
	global_load_dwordx4 v[26:29], v[26:27], off nt
	s_nop 0
	global_load_dwordx4 v[30:33], v[30:31], off nt
	v_add_co_u32_e32 v60, vcc, s15, v58
	global_load_dwordx4 v[34:37], v[34:35], off nt
	s_nop 0
	global_load_dwordx4 v[38:41], v[38:39], off nt
	v_addc_co_u32_e32 v61, vcc, 0, v59, vcc
	s_mov_b32 s15, 0x272000
	global_load_dwordx4 v[42:45], v[42:43], off nt
	s_nop 0
	global_load_dwordx4 v[46:49], v[46:47], off nt
	v_add_co_u32_e32 v62, vcc, s15, v58
	global_load_dwordx4 v[50:53], v[50:51], off nt
	s_nop 0
	global_load_dwordx4 v[54:57], v[54:55], off nt
	v_addc_co_u32_e32 v63, vcc, 0, v59, vcc
	global_load_dwordx4 v[58:61], v[60:61], off nt
	s_nop 0
	global_load_dwordx4 v[62:65], v[62:63], off nt
	s_waitcnt vmcnt(14)
	v_cvt_pk_bf16_f32 v2, v2, v6
	v_cvt_pk_bf16_f32 v3, v3, v7
	v_cvt_pk_bf16_f32 v4, v4, v8
	v_cvt_pk_bf16_f32 v5, v5, v9
	ds_write_b128 v94, v[2:5]
	s_waitcnt vmcnt(12)
	v_cvt_pk_bf16_f32 v2, v10, v14
	v_cvt_pk_bf16_f32 v3, v11, v15
	v_cvt_pk_bf16_f32 v4, v12, v16
	v_cvt_pk_bf16_f32 v5, v13, v17
	ds_write_b128 v94, v[2:5] offset:1088
	s_waitcnt vmcnt(10)
	v_cvt_pk_bf16_f32 v2, v18, v22
	v_cvt_pk_bf16_f32 v3, v19, v23
	v_cvt_pk_bf16_f32 v4, v20, v24
	v_cvt_pk_bf16_f32 v5, v21, v25
	ds_write_b128 v94, v[2:5] offset:2176
	s_waitcnt vmcnt(8)
	v_cvt_pk_bf16_f32 v2, v26, v30
	v_cvt_pk_bf16_f32 v3, v27, v31
	v_cvt_pk_bf16_f32 v4, v28, v32
	v_cvt_pk_bf16_f32 v5, v29, v33
	ds_write_b128 v94, v[2:5] offset:3264
	s_waitcnt vmcnt(6)
	v_cvt_pk_bf16_f32 v2, v34, v38
	v_cvt_pk_bf16_f32 v3, v35, v39
	v_cvt_pk_bf16_f32 v4, v36, v40
	v_cvt_pk_bf16_f32 v5, v37, v41
	ds_write_b128 v94, v[2:5] offset:4352
	s_waitcnt vmcnt(4)
	v_cvt_pk_bf16_f32 v2, v42, v46
	v_cvt_pk_bf16_f32 v3, v43, v47
	v_cvt_pk_bf16_f32 v4, v44, v48
	v_cvt_pk_bf16_f32 v5, v45, v49
	ds_write_b128 v94, v[2:5] offset:5440
	s_waitcnt vmcnt(2)
	v_cvt_pk_bf16_f32 v2, v50, v54
	v_cvt_pk_bf16_f32 v3, v51, v55
	v_cvt_pk_bf16_f32 v4, v52, v56
	v_cvt_pk_bf16_f32 v5, v53, v57
	ds_write_b128 v94, v[2:5] offset:6528
	s_waitcnt vmcnt(0)
	v_cvt_pk_bf16_f32 v2, v58, v62
	v_cvt_pk_bf16_f32 v3, v59, v63
	v_cvt_pk_bf16_f32 v4, v60, v64
	v_cvt_pk_bf16_f32 v5, v61, v65
	ds_write_b128 v94, v[2:5] offset:7616
	s_waitcnt lgkmcnt(0)
	v_add_u32_e32 v14, v95, v96
	ds_read_b128 v[2:5], v14
	ds_read_b128 v[6:9], v14 offset:272
	ds_read_b128 v[10:13], v14 offset:544
	ds_read_b128 v[14:17], v14 offset:816
	v_add_u32_e32 v18, s14, v107
	v_add_u32_e32 v24, 0x114000, v18
	v_ashrrev_i32_e32 v25, 31, v24
	v_lshl_add_u64 v[22:23], s[4:5], 1, v[76:77]
	s_waitcnt lgkmcnt(3)
	v_mov_b32_e32 v18, v2
	v_lshlrev_b64 v[24:25], 9, v[24:25]
	v_add_u32_e32 v2, s14, v106
	s_waitcnt lgkmcnt(2)
	v_mov_b32_e32 v19, v6
	s_waitcnt lgkmcnt(1)
	v_mov_b32_e32 v20, v10
	s_waitcnt lgkmcnt(0)
	v_mov_b32_e32 v21, v14
	v_lshl_add_u64 v[24:25], v[22:23], 0, v[24:25]
	v_add_u32_e32 v2, 0x114000, v2
	global_store_dwordx4 v[24:25], v[18:21], off
	v_mov_b32_e32 v14, v5
	s_nop 0
	v_mov_b32_e32 v18, v3
	v_ashrrev_i32_e32 v3, 31, v2
	v_lshlrev_b64 v[2:3], 9, v[2:3]
	v_mov_b32_e32 v19, v7
	v_mov_b32_e32 v20, v11
	v_mov_b32_e32 v21, v15
	v_lshl_add_u64 v[2:3], v[22:23], 0, v[2:3]
	global_store_dwordx4 v[2:3], v[18:21], off
	v_add_u32_e32 v2, s14, v105
	v_add_u32_e32 v2, 0x114000, v2
	v_ashrrev_i32_e32 v3, 31, v2
	v_lshlrev_b64 v[2:3], 9, v[2:3]
	v_mov_b32_e32 v18, v4
	v_mov_b32_e32 v19, v8
	v_mov_b32_e32 v20, v12
	v_mov_b32_e32 v21, v16
	v_lshl_add_u64 v[2:3], v[22:23], 0, v[2:3]
	global_store_dwordx4 v[2:3], v[18:21], off
	v_add_u32_e32 v2, s14, v104
	v_add_u32_e32 v2, 0x114000, v2
	v_ashrrev_i32_e32 v3, 31, v2
	v_lshlrev_b64 v[2:3], 9, v[2:3]
	v_mov_b32_e32 v15, v9
	v_mov_b32_e32 v16, v13
	v_lshl_add_u64 v[2:3], v[22:23], 0, v[2:3]
	global_store_dwordx4 v[2:3], v[14:17], off
	v_add_u32_e32 v18, s14, v103
	v_add_u32_e32 v24, 0x114000, v18
	v_add_u32_e32 v14, v98, v96
	ds_read_b128 v[2:5], v14
	ds_read_b128 v[6:9], v14 offset:272
	ds_read_b128 v[10:13], v14 offset:544
	ds_read_b128 v[14:17], v14 offset:816
	v_ashrrev_i32_e32 v25, 31, v24
	s_waitcnt lgkmcnt(3)
	v_mov_b32_e32 v18, v2
	v_lshlrev_b64 v[24:25], 9, v[24:25]
	v_add_u32_e32 v2, s14, v102
	s_waitcnt lgkmcnt(2)
	v_mov_b32_e32 v19, v6
	s_waitcnt lgkmcnt(1)
	v_mov_b32_e32 v20, v10
	s_waitcnt lgkmcnt(0)
	v_mov_b32_e32 v21, v14
	v_lshl_add_u64 v[24:25], v[22:23], 0, v[24:25]
	v_add_u32_e32 v2, 0x114000, v2
	global_store_dwordx4 v[24:25], v[18:21], off
	v_mov_b32_e32 v14, v5
	s_nop 0
	v_mov_b32_e32 v18, v3
	v_ashrrev_i32_e32 v3, 31, v2
	v_lshlrev_b64 v[2:3], 9, v[2:3]
	v_mov_b32_e32 v19, v7
	v_mov_b32_e32 v20, v11
	v_mov_b32_e32 v21, v15
	v_lshl_add_u64 v[2:3], v[22:23], 0, v[2:3]
	global_store_dwordx4 v[2:3], v[18:21], off
	v_add_u32_e32 v2, s14, v101
	v_add_u32_e32 v2, 0x114000, v2
	v_ashrrev_i32_e32 v3, 31, v2
	v_lshlrev_b64 v[2:3], 9, v[2:3]
	v_mov_b32_e32 v18, v4
	v_mov_b32_e32 v19, v8
	v_mov_b32_e32 v20, v12
	v_mov_b32_e32 v21, v16
	v_lshl_add_u64 v[2:3], v[22:23], 0, v[2:3]
	global_store_dwordx4 v[2:3], v[18:21], off
	v_add_u32_e32 v2, s14, v100
	v_add_u32_e32 v2, 0x114000, v2
	v_ashrrev_i32_e32 v3, 31, v2
	v_lshlrev_b64 v[2:3], 9, v[2:3]
	v_mov_b32_e32 v15, v9
	v_mov_b32_e32 v16, v13
	v_lshl_add_u64 v[2:3], v[22:23], 0, v[2:3]
	global_store_dwordx4 v[2:3], v[14:17], off
	s_waitcnt lgkmcnt(0)

.LBB0_30:
	s_andn2_b64 vcc, exec, s[14:15]
	s_cbranch_vccnz .LBB0_32
	s_lshl_b32 s4, s30, 6
	s_mov_b64 s[14:15], s[0:1]
	s_and_b32 s53, s4, 0xfffff800
	s_lshl_b32 s4, s11, 1
	s_load_dwordx2 s[16:17], s[14:15], 0x60
	s_addk_i32 s4, 0x2700
	s_andn2_b32 s4, s4, 63
	s_sub_i32 s53, s21, s53
	v_or_b32_e32 v2, s4, v67
	s_add_i32 s54, s53, 0x4e000
	v_lshlrev_b32_e32 v70, 11, v2
	s_waitcnt lgkmcnt(0)
	v_lshl_add_u64 v[2:3], v[70:71], 2, s[16:17]
	s_ashr_i32 s55, s54, 31
	v_lshl_add_u64 v[2:3], s[54:55], 2, v[2:3]
	v_lshlrev_b32_e32 v70, 2, v68
	v_lshl_add_u64 v[62:63], v[2:3], 0, v[70:71]
	v_add_co_u32_e32 v6, vcc, s64, v62
	s_mov_b64 s[14:15], s[0:1]
	s_nop 0
	v_addc_co_u32_e32 v7, vcc, 0, v63, vcc
	v_add_co_u32_e32 v10, vcc, s80, v62
	s_load_dwordx2 s[14:15], s[14:15], 0x10
	s_nop 0
	v_addc_co_u32_e32 v11, vcc, 0, v63, vcc
	v_add_co_u32_e32 v14, vcc, s81, v62
	v_or_b32_e32 v70, s4, v93
	s_nop 0
	v_addc_co_u32_e32 v15, vcc, 0, v63, vcc
	v_add_co_u32_e32 v18, vcc, s67, v62
	s_waitcnt lgkmcnt(0)
	v_lshl_add_u64 v[50:51], v[70:71], 2, s[14:15]
	v_addc_co_u32_e32 v19, vcc, 0, v63, vcc
	v_add_co_u32_e32 v22, vcc, s82, v62
	v_lshl_add_u64 v[64:65], v[50:51], 0, s[6:7]
	s_nop 0
	v_addc_co_u32_e32 v23, vcc, 0, v63, vcc
	v_add_co_u32_e32 v26, vcc, s83, v62
	global_load_dwordx4 v[2:5], v[62:63], off nt
	s_nop 0
	global_load_dwordx4 v[6:9], v[6:7], off nt
	v_addc_co_u32_e32 v27, vcc, 0, v63, vcc
	v_add_co_u32_e32 v30, vcc, s84, v62
	global_load_dwordx4 v[10:13], v[10:11], off nt
	s_nop 0
	global_load_dwordx4 v[14:17], v[14:15], off nt
	v_addc_co_u32_e32 v31, vcc, 0, v63, vcc
	v_add_co_u32_e32 v34, vcc, s71, v62
	global_load_dwordx4 v[18:21], v[18:19], off nt
	s_nop 0
	global_load_dwordx4 v[22:25], v[22:23], off nt
	v_addc_co_u32_e32 v35, vcc, 0, v63, vcc
	v_add_co_u32_e32 v38, vcc, s85, v62
	global_load_dwordx4 v[26:29], v[26:27], off nt
	s_nop 0
	global_load_dwordx4 v[30:33], v[30:31], off nt
	v_addc_co_u32_e32 v39, vcc, 0, v63, vcc
	v_add_co_u32_e32 v42, vcc, s86, v62
	global_load_dwordx4 v[34:37], v[34:35], off nt
	s_nop 0
	global_load_dwordx4 v[38:41], v[38:39], off nt
	v_addc_co_u32_e32 v43, vcc, 0, v63, vcc
	v_add_co_u32_e32 v46, vcc, s87, v62
	s_add_i32 s14, s53, 0xfff3a000
	s_nop 0
	v_addc_co_u32_e32 v47, vcc, 0, v63, vcc
	v_add_co_u32_e32 v44, vcc, s64, v50
	s_nop 1
	v_addc_co_u32_e32 v45, vcc, 0, v51, vcc
	v_add_co_u32_e32 v50, vcc, s73, v62
	global_load_dwordx2 v[148:149], v[44:45], off
	s_nop 0
	global_load_dwordx4 v[42:45], v[42:43], off nt
	s_nop 0
	global_load_dwordx4 v[46:49], v[46:47], off nt
	v_addc_co_u32_e32 v51, vcc, 0, v63, vcc
	v_add_co_u32_e32 v54, vcc, s88, v62
	global_load_dwordx2 v[150:151], v[64:65], off offset:32
	global_load_dwordx2 v[152:153], v[64:65], off offset:64
	v_addc_co_u32_e32 v55, vcc, 0, v63, vcc
	global_load_dwordx2 v[154:155], v[64:65], off offset:96
	v_add_co_u32_e32 v58, vcc, s89, v62
	global_load_dwordx2 v[156:157], v[64:65], off offset:128
	s_nop 0
	global_load_dwordx4 v[50:53], v[50:51], off nt
	s_nop 0
	global_load_dwordx4 v[54:57], v[54:55], off nt
	s_nop 0
	global_load_dwordx2 v[158:159], v[64:65], off offset:160
	v_addc_co_u32_e32 v59, vcc, 0, v63, vcc
	v_add_co_u32_e32 v62, vcc, s90, v62
	global_load_dwordx4 v[58:61], v[58:59], off nt
	s_nop 0
	global_load_dwordx2 v[160:161], v[64:65], off offset:192
	global_load_dwordx2 v[162:163], v[64:65], off offset:224
	v_addc_co_u32_e32 v63, vcc, 0, v63, vcc
	global_load_dwordx4 v[62:65], v[62:63], off nt
	s_waitcnt vmcnt(13)
	v_pk_mul_f32 v[4:5], v[4:5], v[148:149] op_sel_hi:[1,0]
	v_pk_mul_f32 v[2:3], v[2:3], v[148:149] op_sel_hi:[1,0]
	v_pk_mul_f32 v[8:9], v[8:9], v[148:149] op_sel:[0,1]
	v_pk_mul_f32 v[6:7], v[6:7], v[148:149] op_sel:[0,1]
	s_waitcnt vmcnt(10)
	v_pk_mul_f32 v[12:13], v[12:13], v[150:151] op_sel_hi:[1,0]
	v_cvt_pk_bf16_f32 v2, v2, v6
	v_cvt_pk_bf16_f32 v3, v3, v7
	v_cvt_pk_bf16_f32 v4, v4, v8
	v_cvt_pk_bf16_f32 v5, v5, v9
	v_pk_mul_f32 v[10:11], v[10:11], v[150:151] op_sel_hi:[1,0]
	v_pk_mul_f32 v[16:17], v[16:17], v[150:151] op_sel:[0,1]
	v_pk_mul_f32 v[14:15], v[14:15], v[150:151] op_sel:[0,1]
	ds_write_b128 v94, v[2:5]
	v_cvt_pk_bf16_f32 v2, v10, v14
	v_cvt_pk_bf16_f32 v3, v11, v15
	v_cvt_pk_bf16_f32 v4, v12, v16
	v_cvt_pk_bf16_f32 v5, v13, v17
	s_waitcnt vmcnt(9)
	v_pk_mul_f32 v[20:21], v[20:21], v[152:153] op_sel_hi:[1,0]
	v_pk_mul_f32 v[18:19], v[18:19], v[152:153] op_sel_hi:[1,0]
	v_pk_mul_f32 v[24:25], v[24:25], v[152:153] op_sel:[0,1]
	v_pk_mul_f32 v[22:23], v[22:23], v[152:153] op_sel:[0,1]
	ds_write_b128 v94, v[2:5] offset:1088
	v_cvt_pk_bf16_f32 v2, v18, v22
	v_cvt_pk_bf16_f32 v3, v19, v23
	v_cvt_pk_bf16_f32 v4, v20, v24
	v_cvt_pk_bf16_f32 v5, v21, v25
	s_waitcnt vmcnt(8)
	v_pk_mul_f32 v[28:29], v[28:29], v[154:155] op_sel_hi:[1,0]
	v_pk_mul_f32 v[26:27], v[26:27], v[154:155] op_sel_hi:[1,0]
	v_pk_mul_f32 v[32:33], v[32:33], v[154:155] op_sel:[0,1]
	v_pk_mul_f32 v[30:31], v[30:31], v[154:155] op_sel:[0,1]
	ds_write_b128 v94, v[2:5] offset:2176
	v_cvt_pk_bf16_f32 v2, v26, v30
	v_cvt_pk_bf16_f32 v3, v27, v31
	v_cvt_pk_bf16_f32 v4, v28, v32
	v_cvt_pk_bf16_f32 v5, v29, v33
	s_waitcnt vmcnt(7)
	v_pk_mul_f32 v[36:37], v[36:37], v[156:157] op_sel_hi:[1,0]
	v_pk_mul_f32 v[34:35], v[34:35], v[156:157] op_sel_hi:[1,0]
	v_pk_mul_f32 v[40:41], v[40:41], v[156:157] op_sel:[0,1]
	v_pk_mul_f32 v[38:39], v[38:39], v[156:157] op_sel:[0,1]
	ds_write_b128 v94, v[2:5] offset:3264
	v_cvt_pk_bf16_f32 v2, v34, v38
	v_cvt_pk_bf16_f32 v3, v35, v39
	v_cvt_pk_bf16_f32 v4, v36, v40
	v_cvt_pk_bf16_f32 v5, v37, v41
	s_waitcnt vmcnt(4)
	v_pk_mul_f32 v[44:45], v[44:45], v[158:159] op_sel_hi:[1,0]
	v_pk_mul_f32 v[42:43], v[42:43], v[158:159] op_sel_hi:[1,0]
	v_pk_mul_f32 v[48:49], v[48:49], v[158:159] op_sel:[0,1]
	v_pk_mul_f32 v[46:47], v[46:47], v[158:159] op_sel:[0,1]
	ds_write_b128 v94, v[2:5] offset:4352
	v_cvt_pk_bf16_f32 v2, v42, v46
	v_cvt_pk_bf16_f32 v3, v43, v47
	v_cvt_pk_bf16_f32 v4, v44, v48
	v_cvt_pk_bf16_f32 v5, v45, v49
	s_waitcnt vmcnt(2)
	v_pk_mul_f32 v[52:53], v[52:53], v[160:161] op_sel_hi:[1,0]
	v_pk_mul_f32 v[50:51], v[50:51], v[160:161] op_sel_hi:[1,0]
	v_pk_mul_f32 v[56:57], v[56:57], v[160:161] op_sel:[0,1]
	v_pk_mul_f32 v[54:55], v[54:55], v[160:161] op_sel:[0,1]
	ds_write_b128 v94, v[2:5] offset:5440
	v_cvt_pk_bf16_f32 v2, v50, v54
	v_cvt_pk_bf16_f32 v3, v51, v55
	v_cvt_pk_bf16_f32 v4, v52, v56
	v_cvt_pk_bf16_f32 v5, v53, v57
	s_waitcnt vmcnt(1)
	v_pk_mul_f32 v[60:61], v[60:61], v[162:163] op_sel_hi:[1,0]
	v_pk_mul_f32 v[58:59], v[58:59], v[162:163] op_sel_hi:[1,0]
	s_waitcnt vmcnt(0)
	v_pk_mul_f32 v[64:65], v[64:65], v[162:163] op_sel:[0,1]
	v_pk_mul_f32 v[62:63], v[62:63], v[162:163] op_sel:[0,1]
	ds_write_b128 v94, v[2:5] offset:6528
	v_cvt_pk_bf16_f32 v2, v58, v62
	v_cvt_pk_bf16_f32 v3, v59, v63
	v_cvt_pk_bf16_f32 v4, v60, v64
	v_cvt_pk_bf16_f32 v5, v61, v65
	ds_write_b128 v94, v[2:5] offset:7616
	s_waitcnt lgkmcnt(0)
	v_add_u32_e32 v14, v95, v96
	ds_read_b128 v[2:5], v14
	ds_read_b128 v[6:9], v14 offset:272
	ds_read_b128 v[10:13], v14 offset:544
	ds_read_b128 v[14:17], v14 offset:816
	v_add_u32_e32 v18, s14, v115
	v_add_u32_e32 v24, 0x1da000, v18
	v_ashrrev_i32_e32 v25, 31, v24
	v_lshl_add_u64 v[22:23], s[4:5], 1, v[78:79]
	s_waitcnt lgkmcnt(3)
	v_mov_b32_e32 v18, v2
	v_lshlrev_b64 v[24:25], 12, v[24:25]
	v_add_u32_e32 v2, s14, v114
	s_waitcnt lgkmcnt(2)
	v_mov_b32_e32 v19, v6
	s_waitcnt lgkmcnt(1)
	v_mov_b32_e32 v20, v10
	s_waitcnt lgkmcnt(0)
	v_mov_b32_e32 v21, v14
	v_lshl_add_u64 v[24:25], v[22:23], 0, v[24:25]
	v_add_u32_e32 v2, 0x1da000, v2
	global_store_dwordx4 v[24:25], v[18:21], off
	v_mov_b32_e32 v14, v5
	s_nop 0
	v_mov_b32_e32 v18, v3
	v_ashrrev_i32_e32 v3, 31, v2
	v_lshlrev_b64 v[2:3], 12, v[2:3]
	v_mov_b32_e32 v19, v7
	v_mov_b32_e32 v20, v11
	v_mov_b32_e32 v21, v15
	v_lshl_add_u64 v[2:3], v[22:23], 0, v[2:3]
	global_store_dwordx4 v[2:3], v[18:21], off
	v_add_u32_e32 v2, s14, v113
	v_add_u32_e32 v2, 0x1da000, v2
	v_ashrrev_i32_e32 v3, 31, v2
	v_lshlrev_b64 v[2:3], 12, v[2:3]
	v_mov_b32_e32 v18, v4
	v_mov_b32_e32 v19, v8
	v_mov_b32_e32 v20, v12
	v_mov_b32_e32 v21, v16
	v_lshl_add_u64 v[2:3], v[22:23], 0, v[2:3]
	global_store_dwordx4 v[2:3], v[18:21], off
	v_add_u32_e32 v2, s14, v112
	v_add_u32_e32 v2, 0x1da000, v2
	v_ashrrev_i32_e32 v3, 31, v2
	v_lshlrev_b64 v[2:3], 12, v[2:3]
	v_mov_b32_e32 v15, v9
	v_mov_b32_e32 v16, v13
	v_lshl_add_u64 v[2:3], v[22:23], 0, v[2:3]
	global_store_dwordx4 v[2:3], v[14:17], off
	v_add_u32_e32 v18, s14, v111
	v_add_u32_e32 v24, 0x1da000, v18
	v_add_u32_e32 v14, v98, v96
	ds_read_b128 v[2:5], v14
	ds_read_b128 v[6:9], v14 offset:272
	ds_read_b128 v[10:13], v14 offset:544
	ds_read_b128 v[14:17], v14 offset:816
	v_ashrrev_i32_e32 v25, 31, v24
	s_waitcnt lgkmcnt(3)
	v_mov_b32_e32 v18, v2
	v_lshlrev_b64 v[24:25], 12, v[24:25]
	v_add_u32_e32 v2, s14, v110
	s_waitcnt lgkmcnt(2)
	v_mov_b32_e32 v19, v6
	s_waitcnt lgkmcnt(1)
	v_mov_b32_e32 v20, v10
	s_waitcnt lgkmcnt(0)
	v_mov_b32_e32 v21, v14
	v_lshl_add_u64 v[24:25], v[22:23], 0, v[24:25]
	v_add_u32_e32 v2, 0x1da000, v2
	global_store_dwordx4 v[24:25], v[18:21], off
	v_mov_b32_e32 v14, v5
	s_nop 0
	v_mov_b32_e32 v18, v3
	v_ashrrev_i32_e32 v3, 31, v2
	v_lshlrev_b64 v[2:3], 12, v[2:3]
	v_mov_b32_e32 v19, v7
	v_mov_b32_e32 v20, v11
	v_mov_b32_e32 v21, v15
	v_lshl_add_u64 v[2:3], v[22:23], 0, v[2:3]
	global_store_dwordx4 v[2:3], v[18:21], off
	v_add_u32_e32 v2, s14, v109
	v_add_u32_e32 v2, 0x1da000, v2
	v_ashrrev_i32_e32 v3, 31, v2
	v_lshlrev_b64 v[2:3], 12, v[2:3]
	v_mov_b32_e32 v18, v4
	v_mov_b32_e32 v19, v8
	v_mov_b32_e32 v20, v12
	v_mov_b32_e32 v21, v16
	v_lshl_add_u64 v[2:3], v[22:23], 0, v[2:3]
	global_store_dwordx4 v[2:3], v[18:21], off
	v_add_u32_e32 v2, s14, v108
	v_add_u32_e32 v2, 0x1da000, v2
	v_ashrrev_i32_e32 v3, 31, v2
	v_lshlrev_b64 v[2:3], 12, v[2:3]
	v_mov_b32_e32 v15, v9
	v_mov_b32_e32 v16, v13
	v_lshl_add_u64 v[2:3], v[22:23], 0, v[2:3]
	global_store_dwordx4 v[2:3], v[14:17], off
	s_waitcnt lgkmcnt(0)

.LBB0_33:
	s_andn2_b64 vcc, exec, s[14:15]
	s_cbranch_vccnz .LBB0_37
	s_lshl_b32 s4, s31, 6
	s_and_b32 s4, s4, 0xfffff800
	s_mov_b64 s[14:15], s[0:1]
	s_sub_i32 s16, 0xfff4a000, s4
	s_lshl_b32 s4, s11, 1
	s_load_dwordx2 s[54:55], s[14:15], 0xc8
	s_addk_i32 s4, 0x2f00
	s_andn2_b32 s4, s4, 63
	s_add_i32 s16, s21, s16
	v_or_b32_e32 v2, s4, v67
	s_add_i32 vcc_lo, s16, 0x114000
	v_lshlrev_b32_e32 v70, 11, v2
	s_waitcnt lgkmcnt(0)
	v_lshl_add_u64 v[2:3], v[70:71], 2, s[54:55]
	s_ashr_i32 vcc_hi, vcc_lo, 31
	v_lshl_add_u64 v[2:3], vcc, 2, v[2:3]
	v_lshlrev_b32_e32 v70, 2, v68
	v_lshl_add_u64 v[2:3], v[2:3], 0, v[70:71]
	v_add_co_u32_e32 v4, vcc, s64, v2
	s_mov_b64 s[14:15], s[0:1]
	s_nop 0
	v_addc_co_u32_e32 v5, vcc, 0, v3, vcc
	global_load_dwordx4 v[58:61], v[2:3], off nt
	global_load_dwordx4 v[62:65], v[4:5], off nt
	v_add_co_u32_e32 v4, vcc, s80, v2
	s_nop 1
	v_addc_co_u32_e32 v5, vcc, 0, v3, vcc
	v_add_co_u32_e32 v6, vcc, s81, v2
	s_nop 1
	v_addc_co_u32_e32 v7, vcc, 0, v3, vcc
	global_load_dwordx4 v[50:53], v[4:5], off nt
	global_load_dwordx4 v[54:57], v[6:7], off nt
	v_add_co_u32_e32 v4, vcc, s67, v2
	s_nop 1
	v_addc_co_u32_e32 v5, vcc, 0, v3, vcc
	v_add_co_u32_e32 v6, vcc, s82, v2
	s_nop 1
	v_addc_co_u32_e32 v7, vcc, 0, v3, vcc
	global_load_dwordx4 v[42:45], v[4:5], off nt
	global_load_dwordx4 v[46:49], v[6:7], off nt
	v_add_co_u32_e32 v4, vcc, s83, v2
	s_nop 1
	v_addc_co_u32_e32 v5, vcc, 0, v3, vcc
	v_add_co_u32_e32 v6, vcc, s84, v2
	s_nop 1
	v_addc_co_u32_e32 v7, vcc, 0, v3, vcc
	global_load_dwordx4 v[34:37], v[4:5], off nt
	global_load_dwordx4 v[38:41], v[6:7], off nt
	v_add_co_u32_e32 v4, vcc, s71, v2
	s_nop 1
	v_addc_co_u32_e32 v5, vcc, 0, v3, vcc
	v_add_co_u32_e32 v6, vcc, s85, v2
	s_nop 1
	v_addc_co_u32_e32 v7, vcc, 0, v3, vcc
	global_load_dwordx4 v[22:25], v[4:5], off nt
	global_load_dwordx4 v[30:33], v[6:7], off nt
	v_add_co_u32_e32 v4, vcc, s86, v2
	s_nop 1
	v_addc_co_u32_e32 v5, vcc, 0, v3, vcc
	v_add_co_u32_e32 v6, vcc, s87, v2
	s_nop 1
	v_addc_co_u32_e32 v7, vcc, 0, v3, vcc
	global_load_dwordx4 v[14:17], v[4:5], off nt
	global_load_dwordx4 v[26:29], v[6:7], off nt
	v_add_co_u32_e32 v4, vcc, s73, v2
	s_nop 1
	v_addc_co_u32_e32 v5, vcc, 0, v3, vcc
	v_add_co_u32_e32 v10, vcc, 0x62000, v2
	s_nop 1
	v_addc_co_u32_e32 v11, vcc, 0, v3, vcc
	global_load_dwordx4 v[6:9], v[4:5], off nt
	global_load_dwordx4 v[18:21], v[10:11], off nt
	v_add_co_u32_e32 v4, vcc, 0x70000, v2
	s_nop 1
	v_addc_co_u32_e32 v5, vcc, 0, v3, vcc
	v_add_co_u32_e32 v10, vcc, 0x72000, v2
	s_nop 1
	v_addc_co_u32_e32 v11, vcc, 0, v3, vcc
	global_load_dwordx4 v[2:5], v[4:5], off nt
	s_nop 0
	global_load_dwordx4 v[10:13], v[10:11], off nt
	s_load_dwordx2 s[14:15], s[14:15], 0x20
	s_waitcnt lgkmcnt(0)
	s_cmp_eq_u64 s[14:15], 0
	s_cbranch_scc1 .LBB0_36
	v_or_b32_e32 v70, s4, v93
	v_lshl_add_u64 v[148:149], v[70:71], 2, s[14:15]
	global_load_dwordx2 v[150:151], v[148:149], off
	global_load_dwordx2 v[152:153], v[148:149], off offset:32
	global_load_dwordx2 v[154:155], v[148:149], off offset:64
	global_load_dwordx2 v[156:157], v[148:149], off offset:96
	global_load_dwordx2 v[158:159], v[148:149], off offset:128
	global_load_dwordx2 v[160:161], v[148:149], off offset:160
	global_load_dwordx2 v[162:163], v[148:149], off offset:192
	s_nop 0
	global_load_dwordx2 v[148:149], v[148:149], off offset:224
	s_waitcnt vmcnt(7)
	v_pk_mul_f32 v[60:61], v[60:61], v[150:151] op_sel_hi:[1,0]
	v_pk_mul_f32 v[58:59], v[58:59], v[150:151] op_sel_hi:[1,0]
	v_pk_mul_f32 v[64:65], v[64:65], v[150:151] op_sel:[0,1]
	v_pk_mul_f32 v[62:63], v[62:63], v[150:151] op_sel:[0,1]
	s_waitcnt vmcnt(6)
	v_pk_mul_f32 v[52:53], v[52:53], v[152:153] op_sel_hi:[1,0]
	v_pk_mul_f32 v[50:51], v[50:51], v[152:153] op_sel_hi:[1,0]
	v_pk_mul_f32 v[56:57], v[56:57], v[152:153] op_sel:[0,1]
	v_pk_mul_f32 v[54:55], v[54:55], v[152:153] op_sel:[0,1]
	s_waitcnt vmcnt(5)
	v_pk_mul_f32 v[44:45], v[44:45], v[154:155] op_sel_hi:[1,0]
	v_pk_mul_f32 v[42:43], v[42:43], v[154:155] op_sel_hi:[1,0]
	v_pk_mul_f32 v[48:49], v[48:49], v[154:155] op_sel:[0,1]
	v_pk_mul_f32 v[46:47], v[46:47], v[154:155] op_sel:[0,1]
	s_waitcnt vmcnt(4)
	v_pk_mul_f32 v[36:37], v[36:37], v[156:157] op_sel_hi:[1,0]
	v_pk_mul_f32 v[34:35], v[34:35], v[156:157] op_sel_hi:[1,0]
	v_pk_mul_f32 v[40:41], v[40:41], v[156:157] op_sel:[0,1]
	v_pk_mul_f32 v[38:39], v[38:39], v[156:157] op_sel:[0,1]
	s_waitcnt vmcnt(3)
	v_pk_mul_f32 v[24:25], v[24:25], v[158:159] op_sel_hi:[1,0]
	v_pk_mul_f32 v[22:23], v[22:23], v[158:159] op_sel_hi:[1,0]
	v_pk_mul_f32 v[32:33], v[32:33], v[158:159] op_sel:[0,1]
	v_pk_mul_f32 v[30:31], v[30:31], v[158:159] op_sel:[0,1]
	s_waitcnt vmcnt(2)
	v_pk_mul_f32 v[16:17], v[16:17], v[160:161] op_sel_hi:[1,0]
	v_pk_mul_f32 v[14:15], v[14:15], v[160:161] op_sel_hi:[1,0]
	v_pk_mul_f32 v[28:29], v[28:29], v[160:161] op_sel:[0,1]
	v_pk_mul_f32 v[26:27], v[26:27], v[160:161] op_sel:[0,1]
	s_waitcnt vmcnt(1)
	v_pk_mul_f32 v[8:9], v[8:9], v[162:163] op_sel_hi:[1,0]
	v_pk_mul_f32 v[6:7], v[6:7], v[162:163] op_sel_hi:[1,0]
	v_pk_mul_f32 v[20:21], v[20:21], v[162:163] op_sel:[0,1]
	v_pk_mul_f32 v[18:19], v[18:19], v[162:163] op_sel:[0,1]
	s_waitcnt vmcnt(0)
	v_pk_mul_f32 v[4:5], v[4:5], v[148:149] op_sel_hi:[1,0]
	v_pk_mul_f32 v[2:3], v[2:3], v[148:149] op_sel_hi:[1,0]
	v_pk_mul_f32 v[12:13], v[12:13], v[148:149] op_sel:[0,1]
	v_pk_mul_f32 v[10:11], v[10:11], v[148:149] op_sel:[0,1]

.LBB0_38:
	s_andn2_b64 vcc, exec, s[14:15]
	s_cbranch_vccnz .LBB0_40
	s_mov_b64 s[14:15], s[0:1]
	s_lshl_b32 s4, s11, 1
	s_load_dwordx2 s[16:17], s[14:15], 0xc0
	s_addk_i32 s4, 0x4500
	s_lshl_b32 s14, s34, 6
	s_andn2_b32 s4, s4, 63
	s_and_b32 s14, s14, 0xfffff800
	s_sub_i32 s14, s21, s14
	v_or_b32_e32 v2, s4, v67
	s_add_i32 s54, s14, 0x8a000
	v_lshlrev_b32_e32 v70, 11, v2
	s_waitcnt lgkmcnt(0)
	v_lshl_add_u64 v[2:3], v[70:71], 2, s[16:17]
	s_ashr_i32 s55, s54, 31
	v_lshl_add_u64 v[2:3], s[54:55], 2, v[2:3]
	v_lshlrev_b32_e32 v70, 2, v68
	v_lshl_add_u64 v[58:59], v[2:3], 0, v[70:71]
	v_add_co_u32_e32 v6, vcc, s64, v58
	s_nop 1
	v_addc_co_u32_e32 v7, vcc, 0, v59, vcc
	v_add_co_u32_e32 v10, vcc, s80, v58
	global_load_dwordx4 v[2:5], v[58:59], off nt
	s_nop 0
	global_load_dwordx4 v[6:9], v[6:7], off nt
	v_addc_co_u32_e32 v11, vcc, 0, v59, vcc
	v_add_co_u32_e32 v14, vcc, s81, v58
	s_nop 1
	v_addc_co_u32_e32 v15, vcc, 0, v59, vcc
	v_add_co_u32_e32 v18, vcc, s67, v58
	global_load_dwordx4 v[10:13], v[10:11], off nt
	s_nop 0
	global_load_dwordx4 v[14:17], v[14:15], off nt
	v_addc_co_u32_e32 v19, vcc, 0, v59, vcc
	v_add_co_u32_e32 v22, vcc, s82, v58
	s_nop 1
	v_addc_co_u32_e32 v23, vcc, 0, v59, vcc
	v_add_co_u32_e32 v26, vcc, s83, v58
	global_load_dwordx4 v[18:21], v[18:19], off nt
	s_nop 0
	global_load_dwordx4 v[22:25], v[22:23], off nt
	v_addc_co_u32_e32 v27, vcc, 0, v59, vcc
	v_add_co_u32_e32 v30, vcc, s84, v58
	s_nop 1
	v_addc_co_u32_e32 v31, vcc, 0, v59, vcc
	v_add_co_u32_e32 v34, vcc, s71, v58
	global_load_dwordx4 v[26:29], v[26:27], off nt
	s_nop 0
	global_load_dwordx4 v[30:33], v[30:31], off nt
	v_addc_co_u32_e32 v35, vcc, 0, v59, vcc
	v_add_co_u32_e32 v38, vcc, s85, v58
	s_nop 1
	v_addc_co_u32_e32 v39, vcc, 0, v59, vcc
	v_add_co_u32_e32 v42, vcc, s86, v58
	global_load_dwordx4 v[34:37], v[34:35], off nt
	s_nop 0
	global_load_dwordx4 v[38:41], v[38:39], off nt
	v_addc_co_u32_e32 v43, vcc, 0, v59, vcc
	v_add_co_u32_e32 v46, vcc, s87, v58
	s_nop 1
	v_addc_co_u32_e32 v47, vcc, 0, v59, vcc
	v_add_co_u32_e32 v50, vcc, s73, v58
	global_load_dwordx4 v[42:45], v[42:43], off nt
	s_nop 0
	global_load_dwordx4 v[46:49], v[46:47], off nt
	v_addc_co_u32_e32 v51, vcc, 0, v59, vcc
	v_add_co_u32_e32 v54, vcc, s88, v58
	s_nop 1
	v_addc_co_u32_e32 v55, vcc, 0, v59, vcc
	v_add_co_u32_e32 v60, vcc, s89, v58
	global_load_dwordx4 v[50:53], v[50:51], off nt
	s_nop 0
	global_load_dwordx4 v[54:57], v[54:55], off nt
	v_addc_co_u32_e32 v61, vcc, 0, v59, vcc
	v_add_co_u32_e32 v62, vcc, s90, v58
	s_nop 1
	v_addc_co_u32_e32 v63, vcc, 0, v59, vcc
	global_load_dwordx4 v[58:61], v[60:61], off nt
	s_nop 0
	global_load_dwordx4 v[62:65], v[62:63], off nt
	s_waitcnt vmcnt(14)
	v_cvt_pk_bf16_f32 v2, v2, v6
	v_cvt_pk_bf16_f32 v3, v3, v7
	v_cvt_pk_bf16_f32 v4, v4, v8
	v_cvt_pk_bf16_f32 v5, v5, v9
	ds_write_b128 v94, v[2:5]
	s_waitcnt vmcnt(12)
	v_cvt_pk_bf16_f32 v2, v10, v14
	v_cvt_pk_bf16_f32 v3, v11, v15
	v_cvt_pk_bf16_f32 v4, v12, v16
	v_cvt_pk_bf16_f32 v5, v13, v17
	ds_write_b128 v94, v[2:5] offset:1088
	s_waitcnt vmcnt(10)
	v_cvt_pk_bf16_f32 v2, v18, v22
	v_cvt_pk_bf16_f32 v3, v19, v23
	v_cvt_pk_bf16_f32 v4, v20, v24
	v_cvt_pk_bf16_f32 v5, v21, v25
	ds_write_b128 v94, v[2:5] offset:2176
	s_waitcnt vmcnt(8)
	v_cvt_pk_bf16_f32 v2, v26, v30
	v_cvt_pk_bf16_f32 v3, v27, v31
	v_cvt_pk_bf16_f32 v4, v28, v32
	v_cvt_pk_bf16_f32 v5, v29, v33
	ds_write_b128 v94, v[2:5] offset:3264
	s_waitcnt vmcnt(6)
	v_cvt_pk_bf16_f32 v2, v34, v38
	v_cvt_pk_bf16_f32 v3, v35, v39
	v_cvt_pk_bf16_f32 v4, v36, v40
	v_cvt_pk_bf16_f32 v5, v37, v41
	ds_write_b128 v94, v[2:5] offset:4352
	s_waitcnt vmcnt(4)
	v_cvt_pk_bf16_f32 v2, v42, v46
	v_cvt_pk_bf16_f32 v3, v43, v47
	v_cvt_pk_bf16_f32 v4, v44, v48
	v_cvt_pk_bf16_f32 v5, v45, v49
	ds_write_b128 v94, v[2:5] offset:5440
	s_waitcnt vmcnt(2)
	v_cvt_pk_bf16_f32 v2, v50, v54
	v_cvt_pk_bf16_f32 v3, v51, v55
	v_cvt_pk_bf16_f32 v4, v52, v56
	v_cvt_pk_bf16_f32 v5, v53, v57
	ds_write_b128 v94, v[2:5] offset:6528
	s_waitcnt vmcnt(0)
	v_cvt_pk_bf16_f32 v2, v58, v62
	v_cvt_pk_bf16_f32 v3, v59, v63
	v_cvt_pk_bf16_f32 v4, v60, v64
	v_cvt_pk_bf16_f32 v5, v61, v65
	ds_write_b128 v94, v[2:5] offset:7616
	s_waitcnt lgkmcnt(0)
	v_add_u32_e32 v14, v95, v96
	ds_read_b128 v[2:5], v14
	ds_read_b128 v[6:9], v14 offset:272
	ds_read_b128 v[10:13], v14 offset:544
	ds_read_b128 v[14:17], v14 offset:816
	v_add_u32_e32 v18, s14, v131
	v_lshl_add_u64 v[22:23], s[4:5], 1, v[82:83]
	v_add_u32_e32 v24, 0x114000, v18
	s_waitcnt lgkmcnt(3)
	v_mov_b32_e32 v18, v2
	v_add_u32_e32 v2, s14, v130
	s_waitcnt lgkmcnt(2)
	v_mov_b32_e32 v19, v6
	s_waitcnt lgkmcnt(1)
	v_mov_b32_e32 v20, v10
	s_waitcnt lgkmcnt(0)
	v_mov_b32_e32 v21, v14
	v_mad_i64_i32 v[24:25], s[16:17], v24, s47, v[22:23]
	v_add_u32_e32 v2, 0x114000, v2
	global_store_dwordx4 v[24:25], v[18:21], off
	v_mov_b32_e32 v14, v5
	s_nop 0
	v_mov_b32_e32 v18, v3
	v_mov_b32_e32 v19, v7
	v_mov_b32_e32 v20, v11
	v_mov_b32_e32 v21, v15
	v_mad_i64_i32 v[2:3], s[16:17], v2, s47, v[22:23]
	global_store_dwordx4 v[2:3], v[18:21], off
	v_add_u32_e32 v2, s14, v129
	v_add_u32_e32 v2, 0x114000, v2
	v_mov_b32_e32 v18, v4
	v_mov_b32_e32 v19, v8
	v_mov_b32_e32 v20, v12
	v_mov_b32_e32 v21, v16
	v_mad_i64_i32 v[2:3], s[16:17], v2, s47, v[22:23]
	global_store_dwordx4 v[2:3], v[18:21], off
	v_add_u32_e32 v2, s14, v128
	v_add_u32_e32 v2, 0x114000, v2
	v_mov_b32_e32 v15, v9
	v_mov_b32_e32 v16, v13
	v_mad_i64_i32 v[2:3], s[16:17], v2, s47, v[22:23]
	global_store_dwordx4 v[2:3], v[14:17], off
	v_add_u32_e32 v18, s14, v127
	v_add_u32_e32 v24, 0x114000, v18
	v_add_u32_e32 v14, v98, v96
	ds_read_b128 v[2:5], v14
	ds_read_b128 v[6:9], v14 offset:272
	ds_read_b128 v[10:13], v14 offset:544
	ds_read_b128 v[14:17], v14 offset:816
	v_mad_i64_i32 v[24:25], s[16:17], v24, s47, v[22:23]
	s_waitcnt lgkmcnt(3)
	v_mov_b32_e32 v18, v2
	v_add_u32_e32 v2, s14, v126
	s_waitcnt lgkmcnt(2)
	v_mov_b32_e32 v19, v6
	s_waitcnt lgkmcnt(1)
	v_mov_b32_e32 v20, v10
	s_waitcnt lgkmcnt(0)
	v_mov_b32_e32 v21, v14
	v_add_u32_e32 v2, 0x114000, v2
	global_store_dwordx4 v[24:25], v[18:21], off
	v_mov_b32_e32 v14, v5
	s_nop 0
	v_mov_b32_e32 v18, v3
	v_mov_b32_e32 v19, v7
	v_mov_b32_e32 v20, v11
	v_mov_b32_e32 v21, v15
	v_mad_i64_i32 v[2:3], s[16:17], v2, s47, v[22:23]
	global_store_dwordx4 v[2:3], v[18:21], off
	v_add_u32_e32 v2, s14, v125
	v_add_u32_e32 v2, 0x114000, v2
	v_mov_b32_e32 v18, v4
	v_mov_b32_e32 v19, v8
	v_mov_b32_e32 v20, v12
	v_mov_b32_e32 v21, v16
	v_mad_i64_i32 v[2:3], s[16:17], v2, s47, v[22:23]
	global_store_dwordx4 v[2:3], v[18:21], off
	v_add_u32_e32 v2, s14, v124
	v_add_u32_e32 v2, 0x114000, v2
	v_mov_b32_e32 v15, v9
	v_mov_b32_e32 v16, v13
	v_mad_i64_i32 v[2:3], s[14:15], v2, s47, v[22:23]
	global_store_dwordx4 v[2:3], v[14:17], off
	s_waitcnt lgkmcnt(0)

.LBB0_41:
	s_andn2_b64 vcc, exec, s[14:15]
	s_cbranch_vccnz .LBB0_43
	s_mov_b64 s[14:15], s[0:1]
	s_lshl_b32 s4, s11, 1
	s_load_dwordx2 s[16:17], s[14:15], 0x58
	s_addk_i32 s4, 0x4d00
	s_lshl_b32 s14, s35, 6
	s_andn2_b32 s4, s4, 63
	s_and_b32 s14, s14, 0xfffff800
	s_sub_i32 s14, s21, s14
	v_or_b32_e32 v2, s4, v67
	s_add_i32 s54, s14, 0x9a000
	v_lshlrev_b32_e32 v70, 11, v2
	s_waitcnt lgkmcnt(0)
	v_lshl_add_u64 v[2:3], v[70:71], 2, s[16:17]
	s_ashr_i32 s55, s54, 31
	v_lshl_add_u64 v[2:3], s[54:55], 2, v[2:3]
	v_lshlrev_b32_e32 v70, 2, v68
	v_lshl_add_u64 v[58:59], v[2:3], 0, v[70:71]
	v_add_co_u32_e32 v6, vcc, s64, v58
	s_nop 1
	v_addc_co_u32_e32 v7, vcc, 0, v59, vcc
	v_add_co_u32_e32 v10, vcc, s80, v58
	global_load_dwordx4 v[2:5], v[58:59], off nt
	s_nop 0
	global_load_dwordx4 v[6:9], v[6:7], off nt
	v_addc_co_u32_e32 v11, vcc, 0, v59, vcc
	v_add_co_u32_e32 v14, vcc, s81, v58
	s_nop 1
	v_addc_co_u32_e32 v15, vcc, 0, v59, vcc
	v_add_co_u32_e32 v18, vcc, s67, v58
	global_load_dwordx4 v[10:13], v[10:11], off nt
	s_nop 0
	global_load_dwordx4 v[14:17], v[14:15], off nt
	v_addc_co_u32_e32 v19, vcc, 0, v59, vcc
	v_add_co_u32_e32 v22, vcc, s82, v58
	s_nop 1
	v_addc_co_u32_e32 v23, vcc, 0, v59, vcc
	v_add_co_u32_e32 v26, vcc, s83, v58
	global_load_dwordx4 v[18:21], v[18:19], off nt
	s_nop 0
	global_load_dwordx4 v[22:25], v[22:23], off nt
	v_addc_co_u32_e32 v27, vcc, 0, v59, vcc
	v_add_co_u32_e32 v30, vcc, s84, v58
	s_nop 1
	v_addc_co_u32_e32 v31, vcc, 0, v59, vcc
	v_add_co_u32_e32 v34, vcc, s71, v58
	global_load_dwordx4 v[26:29], v[26:27], off nt
	s_nop 0
	global_load_dwordx4 v[30:33], v[30:31], off nt
	v_addc_co_u32_e32 v35, vcc, 0, v59, vcc
	v_add_co_u32_e32 v38, vcc, s85, v58
	s_nop 1
	v_addc_co_u32_e32 v39, vcc, 0, v59, vcc
	v_add_co_u32_e32 v42, vcc, s86, v58
	global_load_dwordx4 v[34:37], v[34:35], off nt
	s_nop 0
	global_load_dwordx4 v[38:41], v[38:39], off nt
	v_addc_co_u32_e32 v43, vcc, 0, v59, vcc
	v_add_co_u32_e32 v46, vcc, s87, v58
	s_nop 1
	v_addc_co_u32_e32 v47, vcc, 0, v59, vcc
	v_add_co_u32_e32 v50, vcc, s73, v58
	global_load_dwordx4 v[42:45], v[42:43], off nt
	s_nop 0
	global_load_dwordx4 v[46:49], v[46:47], off nt
	v_addc_co_u32_e32 v51, vcc, 0, v59, vcc
	v_add_co_u32_e32 v54, vcc, s88, v58
	s_nop 1
	v_addc_co_u32_e32 v55, vcc, 0, v59, vcc
	v_add_co_u32_e32 v60, vcc, s89, v58
	global_load_dwordx4 v[50:53], v[50:51], off nt
	s_nop 0
	global_load_dwordx4 v[54:57], v[54:55], off nt
	v_addc_co_u32_e32 v61, vcc, 0, v59, vcc
	v_add_co_u32_e32 v62, vcc, s90, v58
	s_nop 1
	v_addc_co_u32_e32 v63, vcc, 0, v59, vcc
	global_load_dwordx4 v[58:61], v[60:61], off nt
	s_nop 0
	global_load_dwordx4 v[62:65], v[62:63], off nt
	s_waitcnt vmcnt(14)
	v_cvt_pk_bf16_f32 v2, v2, v6
	v_cvt_pk_bf16_f32 v3, v3, v7
	v_cvt_pk_bf16_f32 v4, v4, v8
	v_cvt_pk_bf16_f32 v5, v5, v9
	ds_write_b128 v94, v[2:5]
	s_waitcnt vmcnt(12)
	v_cvt_pk_bf16_f32 v2, v10, v14
	v_cvt_pk_bf16_f32 v3, v11, v15
	v_cvt_pk_bf16_f32 v4, v12, v16
	v_cvt_pk_bf16_f32 v5, v13, v17
	ds_write_b128 v94, v[2:5] offset:1088
	s_waitcnt vmcnt(10)
	v_cvt_pk_bf16_f32 v2, v18, v22
	v_cvt_pk_bf16_f32 v3, v19, v23
	v_cvt_pk_bf16_f32 v4, v20, v24
	v_cvt_pk_bf16_f32 v5, v21, v25
	ds_write_b128 v94, v[2:5] offset:2176
	s_waitcnt vmcnt(8)
	v_cvt_pk_bf16_f32 v2, v26, v30
	v_cvt_pk_bf16_f32 v3, v27, v31
	v_cvt_pk_bf16_f32 v4, v28, v32
	v_cvt_pk_bf16_f32 v5, v29, v33
	ds_write_b128 v94, v[2:5] offset:3264
	s_waitcnt vmcnt(6)
	v_cvt_pk_bf16_f32 v2, v34, v38
	v_cvt_pk_bf16_f32 v3, v35, v39
	v_cvt_pk_bf16_f32 v4, v36, v40
	v_cvt_pk_bf16_f32 v5, v37, v41
	ds_write_b128 v94, v[2:5] offset:4352
	s_waitcnt vmcnt(4)
	v_cvt_pk_bf16_f32 v2, v42, v46
	v_cvt_pk_bf16_f32 v3, v43, v47
	v_cvt_pk_bf16_f32 v4, v44, v48
	v_cvt_pk_bf16_f32 v5, v45, v49
	ds_write_b128 v94, v[2:5] offset:5440
	s_waitcnt vmcnt(2)
	v_cvt_pk_bf16_f32 v2, v50, v54
	v_cvt_pk_bf16_f32 v3, v51, v55
	v_cvt_pk_bf16_f32 v4, v52, v56
	v_cvt_pk_bf16_f32 v5, v53, v57
	ds_write_b128 v94, v[2:5] offset:6528
	s_waitcnt vmcnt(0)
	v_cvt_pk_bf16_f32 v2, v58, v62
	v_cvt_pk_bf16_f32 v3, v59, v63
	v_cvt_pk_bf16_f32 v4, v60, v64
	v_cvt_pk_bf16_f32 v5, v61, v65
	ds_write_b128 v94, v[2:5] offset:7616
	s_waitcnt lgkmcnt(0)
	v_add_u32_e32 v14, v95, v96
	ds_read_b128 v[2:5], v14
	ds_read_b128 v[6:9], v14 offset:272
	ds_read_b128 v[10:13], v14 offset:544
	ds_read_b128 v[14:17], v14 offset:816
	v_add_u32_e32 v18, s14, v139
	v_add_u32_e32 v24, 0x114000, v18
	v_ashrrev_i32_e32 v25, 31, v24
	v_lshl_add_u64 v[22:23], s[4:5], 1, v[84:85]
	s_waitcnt lgkmcnt(3)
	v_mov_b32_e32 v18, v2
	v_lshlrev_b64 v[24:25], 12, v[24:25]
	v_add_u32_e32 v2, s14, v138
	s_waitcnt lgkmcnt(2)
	v_mov_b32_e32 v19, v6
	s_waitcnt lgkmcnt(1)
	v_mov_b32_e32 v20, v10
	s_waitcnt lgkmcnt(0)
	v_mov_b32_e32 v21, v14
	v_lshl_add_u64 v[24:25], v[22:23], 0, v[24:25]
	v_add_u32_e32 v2, 0x114000, v2
	global_store_dwordx4 v[24:25], v[18:21], off
	v_mov_b32_e32 v14, v5
	s_nop 0
	v_mov_b32_e32 v18, v3
	v_ashrrev_i32_e32 v3, 31, v2
	v_lshlrev_b64 v[2:3], 12, v[2:3]
	v_mov_b32_e32 v19, v7
	v_mov_b32_e32 v20, v11
	v_mov_b32_e32 v21, v15
	v_lshl_add_u64 v[2:3], v[22:23], 0, v[2:3]
	global_store_dwordx4 v[2:3], v[18:21], off
	v_add_u32_e32 v2, s14, v137
	v_add_u32_e32 v2, 0x114000, v2
	v_ashrrev_i32_e32 v3, 31, v2
	v_lshlrev_b64 v[2:3], 12, v[2:3]
	v_mov_b32_e32 v18, v4
	v_mov_b32_e32 v19, v8
	v_mov_b32_e32 v20, v12
	v_mov_b32_e32 v21, v16
	v_lshl_add_u64 v[2:3], v[22:23], 0, v[2:3]
	global_store_dwordx4 v[2:3], v[18:21], off
	v_add_u32_e32 v2, s14, v136
	v_add_u32_e32 v2, 0x114000, v2
	v_ashrrev_i32_e32 v3, 31, v2
	v_lshlrev_b64 v[2:3], 12, v[2:3]
	v_mov_b32_e32 v15, v9
	v_mov_b32_e32 v16, v13
	v_lshl_add_u64 v[2:3], v[22:23], 0, v[2:3]
	global_store_dwordx4 v[2:3], v[14:17], off
	v_add_u32_e32 v18, s14, v135
	v_add_u32_e32 v24, 0x114000, v18
	v_add_u32_e32 v14, v98, v96
	ds_read_b128 v[2:5], v14
	ds_read_b128 v[6:9], v14 offset:272
	ds_read_b128 v[10:13], v14 offset:544
	ds_read_b128 v[14:17], v14 offset:816
	v_ashrrev_i32_e32 v25, 31, v24
	s_waitcnt lgkmcnt(3)
	v_mov_b32_e32 v18, v2
	v_lshlrev_b64 v[24:25], 12, v[24:25]
	v_add_u32_e32 v2, s14, v134
	s_waitcnt lgkmcnt(2)
	v_mov_b32_e32 v19, v6
	s_waitcnt lgkmcnt(1)
	v_mov_b32_e32 v20, v10
	s_waitcnt lgkmcnt(0)
	v_mov_b32_e32 v21, v14
	v_lshl_add_u64 v[24:25], v[22:23], 0, v[24:25]
	v_add_u32_e32 v2, 0x114000, v2
	global_store_dwordx4 v[24:25], v[18:21], off
	v_mov_b32_e32 v14, v5
	s_nop 0
	v_mov_b32_e32 v18, v3
	v_ashrrev_i32_e32 v3, 31, v2
	v_lshlrev_b64 v[2:3], 12, v[2:3]
	v_mov_b32_e32 v19, v7
	v_mov_b32_e32 v20, v11
	v_mov_b32_e32 v21, v15
	v_lshl_add_u64 v[2:3], v[22:23], 0, v[2:3]
	global_store_dwordx4 v[2:3], v[18:21], off
	v_add_u32_e32 v2, s14, v133
	v_add_u32_e32 v2, 0x114000, v2
	v_ashrrev_i32_e32 v3, 31, v2
	v_lshlrev_b64 v[2:3], 12, v[2:3]
	v_mov_b32_e32 v18, v4
	v_mov_b32_e32 v19, v8
	v_mov_b32_e32 v20, v12
	v_mov_b32_e32 v21, v16
	v_lshl_add_u64 v[2:3], v[22:23], 0, v[2:3]
	global_store_dwordx4 v[2:3], v[18:21], off
	v_add_u32_e32 v2, s14, v132
	v_add_u32_e32 v2, 0x114000, v2
	v_ashrrev_i32_e32 v3, 31, v2
	v_lshlrev_b64 v[2:3], 12, v[2:3]
	v_mov_b32_e32 v15, v9
	v_mov_b32_e32 v16, v13
	v_lshl_add_u64 v[2:3], v[22:23], 0, v[2:3]
	global_store_dwordx4 v[2:3], v[14:17], off
	s_waitcnt lgkmcnt(0)

.LBB0_44:
	s_andn2_b64 vcc, exec, s[14:15]
	s_cbranch_vccnz .LBB0_48
	s_and_b32 s4, 0xffff, s44
	s_mul_hi_u32 s16, s4, 0x2e8ba2f
	s_mul_i32 s4, s11, 0xba2f
	s_mov_b64 s[14:15], s[0:1]
	s_add_i32 s4, s4, 0x24001680
	s_load_dwordx2 vcc, s[14:15], 0xb8
	s_lshr_b32 s4, s4, 16
	s_and_b32 s4, s4, 0xffc0
	s_mul_i32 s17, s16, 0xffffea00
	v_or_b32_e32 v2, s4, v67
	s_add_i32 s17, s21, s17
	v_mul_u32_u24_e32 v2, 0x1600, v2
	s_add_i32 s54, s17, 0xc6000
	v_lshlrev_b32_e32 v70, 2, v2
	s_waitcnt lgkmcnt(0)
	v_lshl_add_u64 v[2:3], vcc, 0, v[70:71]
	s_ashr_i32 s55, s54, 31
	v_lshl_add_u64 v[2:3], s[54:55], 2, v[2:3]
	v_lshlrev_b32_e32 v70, 2, v68
	v_lshl_add_u64 v[2:3], v[2:3], 0, v[70:71]
	v_add_co_u32_e32 v4, vcc, s91, v2
	s_mov_b64 s[14:15], s[0:1]
	s_nop 0
	v_addc_co_u32_e32 v5, vcc, 0, v3, vcc
	global_load_dwordx4 v[58:61], v[2:3], off nt
	global_load_dwordx4 v[62:65], v[4:5], off offset:2048 nt
	v_add_co_u32_e32 v4, vcc, s65, v2
	s_nop 1
	v_addc_co_u32_e32 v5, vcc, 0, v3, vcc
	v_add_co_u32_e32 v6, vcc, s92, v2
	s_nop 1
	v_addc_co_u32_e32 v7, vcc, 0, v3, vcc
	global_load_dwordx4 v[50:53], v[4:5], off nt
	global_load_dwordx4 v[54:57], v[6:7], off offset:2048 nt
	v_add_co_u32_e32 v4, vcc, s93, v2
	s_nop 1
	v_addc_co_u32_e32 v5, vcc, 0, v3, vcc
	v_add_co_u32_e32 v6, vcc, s94, v2
	s_nop 1
	v_addc_co_u32_e32 v7, vcc, 0, v3, vcc
	global_load_dwordx4 v[42:45], v[4:5], off nt
	global_load_dwordx4 v[46:49], v[6:7], off offset:2048 nt
	v_add_co_u32_e32 v4, vcc, s76, v2
	s_nop 1
	v_addc_co_u32_e32 v5, vcc, 0, v3, vcc
	v_add_co_u32_e32 v6, vcc, s95, v2
	s_nop 1
	v_addc_co_u32_e32 v7, vcc, 0, v3, vcc
	global_load_dwordx4 v[34:37], v[4:5], off nt
	global_load_dwordx4 v[38:41], v[6:7], off offset:2048 nt
	v_add_co_u32_e32 v4, vcc, s96, v2
	s_nop 1
	v_addc_co_u32_e32 v5, vcc, 0, v3, vcc
	v_add_co_u32_e32 v6, vcc, s97, v2
	s_nop 1
	v_addc_co_u32_e32 v7, vcc, 0, v3, vcc
	global_load_dwordx4 v[22:25], v[4:5], off nt
	global_load_dwordx4 v[30:33], v[6:7], off offset:2048 nt
	v_add_co_u32_e32 v4, vcc, s48, v2
	s_nop 1
	v_addc_co_u32_e32 v5, vcc, 0, v3, vcc
	v_add_co_u32_e32 v6, vcc, s49, v2
	s_nop 1
	v_addc_co_u32_e32 v7, vcc, 0, v3, vcc
	global_load_dwordx4 v[14:17], v[4:5], off nt
	global_load_dwordx4 v[26:29], v[6:7], off offset:2048 nt
	v_add_co_u32_e32 v4, vcc, s50, v2
	s_nop 1
	v_addc_co_u32_e32 v5, vcc, 0, v3, vcc
	v_add_co_u32_e32 v10, vcc, 0x10d000, v2
	s_nop 1
	v_addc_co_u32_e32 v11, vcc, 0, v3, vcc
	global_load_dwordx4 v[6:9], v[4:5], off nt
	global_load_dwordx4 v[18:21], v[10:11], off offset:2048 nt
	v_add_co_u32_e32 v4, vcc, 0x134000, v2
	s_nop 1
	v_addc_co_u32_e32 v5, vcc, 0, v3, vcc
	v_add_co_u32_e32 v10, vcc, 0x139000, v2
	s_nop 1
	v_addc_co_u32_e32 v11, vcc, 0, v3, vcc
	global_load_dwordx4 v[2:5], v[4:5], off nt
	s_nop 0
	global_load_dwordx4 v[10:13], v[10:11], off offset:2048 nt
	s_load_dwordx2 s[14:15], s[14:15], 0x18
	s_waitcnt lgkmcnt(0)
	s_cmp_eq_u64 s[14:15], 0
	s_cbranch_scc1 .LBB0_47
	v_or_b32_e32 v70, s4, v93
	v_lshlrev_b32_e32 v70, 2, v70
	global_load_dwordx2 v[148:149], v70, s[14:15]
	global_load_dwordx2 v[150:151], v70, s[14:15] offset:32
	global_load_dwordx2 v[152:153], v70, s[14:15] offset:64
	global_load_dwordx2 v[154:155], v70, s[14:15] offset:96
	global_load_dwordx2 v[156:157], v70, s[14:15] offset:128
	global_load_dwordx2 v[158:159], v70, s[14:15] offset:160
	global_load_dwordx2 v[160:161], v70, s[14:15] offset:192
	global_load_dwordx2 v[162:163], v70, s[14:15] offset:224
	s_waitcnt vmcnt(7)
	v_pk_mul_f32 v[60:61], v[60:61], v[148:149] op_sel_hi:[1,0]
	v_pk_mul_f32 v[58:59], v[58:59], v[148:149] op_sel_hi:[1,0]
	v_pk_mul_f32 v[64:65], v[64:65], v[148:149] op_sel:[0,1]
	v_pk_mul_f32 v[62:63], v[62:63], v[148:149] op_sel:[0,1]
	s_waitcnt vmcnt(6)
	v_pk_mul_f32 v[52:53], v[52:53], v[150:151] op_sel_hi:[1,0]
	v_pk_mul_f32 v[50:51], v[50:51], v[150:151] op_sel_hi:[1,0]
	v_pk_mul_f32 v[56:57], v[56:57], v[150:151] op_sel:[0,1]
	v_pk_mul_f32 v[54:55], v[54:55], v[150:151] op_sel:[0,1]
	s_waitcnt vmcnt(5)
	v_pk_mul_f32 v[44:45], v[44:45], v[152:153] op_sel_hi:[1,0]
	v_pk_mul_f32 v[42:43], v[42:43], v[152:153] op_sel_hi:[1,0]
	v_pk_mul_f32 v[48:49], v[48:49], v[152:153] op_sel:[0,1]
	v_pk_mul_f32 v[46:47], v[46:47], v[152:153] op_sel:[0,1]
	s_waitcnt vmcnt(4)
	v_pk_mul_f32 v[36:37], v[36:37], v[154:155] op_sel_hi:[1,0]
	v_pk_mul_f32 v[34:35], v[34:35], v[154:155] op_sel_hi:[1,0]
	v_pk_mul_f32 v[40:41], v[40:41], v[154:155] op_sel:[0,1]
	v_pk_mul_f32 v[38:39], v[38:39], v[154:155] op_sel:[0,1]
	s_waitcnt vmcnt(3)
	v_pk_mul_f32 v[24:25], v[24:25], v[156:157] op_sel_hi:[1,0]
	v_pk_mul_f32 v[22:23], v[22:23], v[156:157] op_sel_hi:[1,0]
	v_pk_mul_f32 v[32:33], v[32:33], v[156:157] op_sel:[0,1]
	v_pk_mul_f32 v[30:31], v[30:31], v[156:157] op_sel:[0,1]
	s_waitcnt vmcnt(2)
	v_pk_mul_f32 v[16:17], v[16:17], v[158:159] op_sel_hi:[1,0]
	v_pk_mul_f32 v[14:15], v[14:15], v[158:159] op_sel_hi:[1,0]
	v_pk_mul_f32 v[28:29], v[28:29], v[158:159] op_sel:[0,1]
	v_pk_mul_f32 v[26:27], v[26:27], v[158:159] op_sel:[0,1]
	s_waitcnt vmcnt(1)
	v_pk_mul_f32 v[8:9], v[8:9], v[160:161] op_sel_hi:[1,0]
	v_pk_mul_f32 v[6:7], v[6:7], v[160:161] op_sel_hi:[1,0]
	v_pk_mul_f32 v[20:21], v[20:21], v[160:161] op_sel:[0,1]
	v_pk_mul_f32 v[18:19], v[18:19], v[160:161] op_sel:[0,1]
	s_waitcnt vmcnt(0)
	v_pk_mul_f32 v[4:5], v[4:5], v[162:163] op_sel_hi:[1,0]
	v_pk_mul_f32 v[2:3], v[2:3], v[162:163] op_sel_hi:[1,0]
	v_pk_mul_f32 v[12:13], v[12:13], v[162:163] op_sel:[0,1]
	v_pk_mul_f32 v[10:11], v[10:11], v[162:163] op_sel:[0,1]

.LBB0_49:
	s_andn2_b64 vcc, exec, s[14:15]
	s_cbranch_vccnz .LBB0_53
	s_and_b32 s4, 0xffff, s46
	s_mul_hi_u32 s53, s4, 0x2e8ba2f
	s_mul_i32 s4, s11, 0xba2f
	s_mov_b64 s[14:15], s[0:1]
	s_add_i32 s4, s4, 0x2c001b80
	s_load_dwordx2 vcc, s[14:15], 0xb0
	s_lshr_b32 s4, s4, 16
	s_and_b32 s4, s4, 0xffc0
	s_mul_i32 s54, s53, 0xffffea00
	v_or_b32_e32 v2, s4, v67
	s_add_i32 s14, s21, s54
	v_mul_u32_u24_e32 v2, 0x1600, v2
	s_add_i32 s14, s14, 0xf2000
	v_lshlrev_b32_e32 v70, 2, v2
	s_waitcnt lgkmcnt(0)
	v_lshl_add_u64 v[2:3], vcc, 0, v[70:71]
	s_ashr_i32 s15, s14, 31
	v_lshl_add_u64 v[2:3], s[14:15], 2, v[2:3]
	v_lshlrev_b32_e32 v70, 2, v68
	v_lshl_add_u64 v[2:3], v[2:3], 0, v[70:71]
	v_add_co_u32_e32 v4, vcc, s91, v2
	s_mov_b64 s[16:17], s[0:1]
	s_nop 0
	v_addc_co_u32_e32 v5, vcc, 0, v3, vcc
	global_load_dwordx4 v[58:61], v[2:3], off nt
	global_load_dwordx4 v[62:65], v[4:5], off offset:2048 nt
	v_add_co_u32_e32 v4, vcc, s65, v2
	s_nop 1
	v_addc_co_u32_e32 v5, vcc, 0, v3, vcc
	v_add_co_u32_e32 v6, vcc, s92, v2
	s_nop 1
	v_addc_co_u32_e32 v7, vcc, 0, v3, vcc
	global_load_dwordx4 v[50:53], v[4:5], off nt
	global_load_dwordx4 v[54:57], v[6:7], off offset:2048 nt
	v_add_co_u32_e32 v4, vcc, s93, v2
	s_nop 1
	v_addc_co_u32_e32 v5, vcc, 0, v3, vcc
	v_add_co_u32_e32 v6, vcc, s94, v2
	s_nop 1
	v_addc_co_u32_e32 v7, vcc, 0, v3, vcc
	global_load_dwordx4 v[42:45], v[4:5], off nt
	global_load_dwordx4 v[46:49], v[6:7], off offset:2048 nt
	v_add_co_u32_e32 v4, vcc, s76, v2
	s_nop 1
	v_addc_co_u32_e32 v5, vcc, 0, v3, vcc
	v_add_co_u32_e32 v6, vcc, s95, v2
	s_nop 1
	v_addc_co_u32_e32 v7, vcc, 0, v3, vcc
	global_load_dwordx4 v[34:37], v[4:5], off nt
	global_load_dwordx4 v[38:41], v[6:7], off offset:2048 nt
	v_add_co_u32_e32 v4, vcc, s96, v2
	s_nop 1
	v_addc_co_u32_e32 v5, vcc, 0, v3, vcc
	v_add_co_u32_e32 v6, vcc, s97, v2
	s_nop 1
	v_addc_co_u32_e32 v7, vcc, 0, v3, vcc
	global_load_dwordx4 v[22:25], v[4:5], off nt
	global_load_dwordx4 v[30:33], v[6:7], off offset:2048 nt
	v_add_co_u32_e32 v4, vcc, s48, v2
	s_nop 1
	v_addc_co_u32_e32 v5, vcc, 0, v3, vcc
	v_add_co_u32_e32 v6, vcc, s49, v2
	s_nop 1
	v_addc_co_u32_e32 v7, vcc, 0, v3, vcc
	global_load_dwordx4 v[14:17], v[4:5], off nt
	global_load_dwordx4 v[26:29], v[6:7], off offset:2048 nt
	v_add_co_u32_e32 v4, vcc, s50, v2
	s_nop 1
	v_addc_co_u32_e32 v5, vcc, 0, v3, vcc
	v_add_co_u32_e32 v10, vcc, 0x10d000, v2
	s_nop 1
	v_addc_co_u32_e32 v11, vcc, 0, v3, vcc
	global_load_dwordx4 v[6:9], v[4:5], off nt
	global_load_dwordx4 v[18:21], v[10:11], off offset:2048 nt
	v_add_co_u32_e32 v4, vcc, 0x134000, v2
	s_nop 1
	v_addc_co_u32_e32 v5, vcc, 0, v3, vcc
	v_add_co_u32_e32 v10, vcc, 0x139000, v2
	s_nop 1
	v_addc_co_u32_e32 v11, vcc, 0, v3, vcc
	global_load_dwordx4 v[2:5], v[4:5], off nt
	s_nop 0
	global_load_dwordx4 v[10:13], v[10:11], off offset:2048 nt
	s_load_dwordx2 s[16:17], s[16:17], 0x18
	s_waitcnt lgkmcnt(0)
	s_cmp_eq_u64 s[16:17], 0
	s_cbranch_scc1 .LBB0_52
	v_or_b32_e32 v70, s4, v93
	v_lshlrev_b32_e32 v70, 2, v70
	global_load_dwordx2 v[148:149], v70, s[16:17]
	global_load_dwordx2 v[150:151], v70, s[16:17] offset:32
	global_load_dwordx2 v[152:153], v70, s[16:17] offset:64
	global_load_dwordx2 v[154:155], v70, s[16:17] offset:96
	global_load_dwordx2 v[156:157], v70, s[16:17] offset:128
	global_load_dwordx2 v[158:159], v70, s[16:17] offset:160
	global_load_dwordx2 v[160:161], v70, s[16:17] offset:192
	global_load_dwordx2 v[162:163], v70, s[16:17] offset:224
	s_waitcnt vmcnt(7)
	v_pk_mul_f32 v[60:61], v[60:61], v[148:149] op_sel_hi:[1,0]
	v_pk_mul_f32 v[58:59], v[58:59], v[148:149] op_sel_hi:[1,0]
	v_pk_mul_f32 v[64:65], v[64:65], v[148:149] op_sel:[0,1]
	v_pk_mul_f32 v[62:63], v[62:63], v[148:149] op_sel:[0,1]
	s_waitcnt vmcnt(6)
	v_pk_mul_f32 v[52:53], v[52:53], v[150:151] op_sel_hi:[1,0]
	v_pk_mul_f32 v[50:51], v[50:51], v[150:151] op_sel_hi:[1,0]
	v_pk_mul_f32 v[56:57], v[56:57], v[150:151] op_sel:[0,1]
	v_pk_mul_f32 v[54:55], v[54:55], v[150:151] op_sel:[0,1]
	s_waitcnt vmcnt(5)
	v_pk_mul_f32 v[44:45], v[44:45], v[152:153] op_sel_hi:[1,0]
	v_pk_mul_f32 v[42:43], v[42:43], v[152:153] op_sel_hi:[1,0]
	v_pk_mul_f32 v[48:49], v[48:49], v[152:153] op_sel:[0,1]
	v_pk_mul_f32 v[46:47], v[46:47], v[152:153] op_sel:[0,1]
	s_waitcnt vmcnt(4)
	v_pk_mul_f32 v[36:37], v[36:37], v[154:155] op_sel_hi:[1,0]
	v_pk_mul_f32 v[34:35], v[34:35], v[154:155] op_sel_hi:[1,0]
	v_pk_mul_f32 v[40:41], v[40:41], v[154:155] op_sel:[0,1]
	v_pk_mul_f32 v[38:39], v[38:39], v[154:155] op_sel:[0,1]
	s_waitcnt vmcnt(3)
	v_pk_mul_f32 v[24:25], v[24:25], v[156:157] op_sel_hi:[1,0]
	v_pk_mul_f32 v[22:23], v[22:23], v[156:157] op_sel_hi:[1,0]
	v_pk_mul_f32 v[32:33], v[32:33], v[156:157] op_sel:[0,1]
	v_pk_mul_f32 v[30:31], v[30:31], v[156:157] op_sel:[0,1]
	s_waitcnt vmcnt(2)
	v_pk_mul_f32 v[16:17], v[16:17], v[158:159] op_sel_hi:[1,0]
	v_pk_mul_f32 v[14:15], v[14:15], v[158:159] op_sel_hi:[1,0]
	v_pk_mul_f32 v[28:29], v[28:29], v[158:159] op_sel:[0,1]
	v_pk_mul_f32 v[26:27], v[26:27], v[158:159] op_sel:[0,1]
	s_waitcnt vmcnt(1)
	v_pk_mul_f32 v[8:9], v[8:9], v[160:161] op_sel_hi:[1,0]
	v_pk_mul_f32 v[6:7], v[6:7], v[160:161] op_sel_hi:[1,0]
	v_pk_mul_f32 v[20:21], v[20:21], v[160:161] op_sel:[0,1]
	v_pk_mul_f32 v[18:19], v[18:19], v[160:161] op_sel:[0,1]
	s_waitcnt vmcnt(0)
	v_pk_mul_f32 v[4:5], v[4:5], v[162:163] op_sel_hi:[1,0]
	v_pk_mul_f32 v[2:3], v[2:3], v[162:163] op_sel_hi:[1,0]
	v_pk_mul_f32 v[12:13], v[12:13], v[162:163] op_sel:[0,1]
	v_pk_mul_f32 v[10:11], v[10:11], v[162:163] op_sel:[0,1]

.LBB0_54:
	s_andn2_b64 vcc, exec, s[14:15]
	s_cbranch_vccnz .LBB0_56
	s_mov_b64 s[14:15], s[0:1]
	s_load_dwordx2 s[16:17], s[14:15], 0xd0
	s_lshl_b32 s14, s51, 6
	s_and_b32 s14, s14, 0x3800
	s_bfe_u32 s4, s52, 0x30005
	s_sub_i32 s14, s21, s14
	v_lshlrev_b32_e32 v2, 13, v67
	s_add_i32 vcc_lo, s14, 0xf4000
	v_lshl_or_b32 v70, s4, 19, v2
	s_waitcnt lgkmcnt(0)
	v_lshl_add_u64 v[2:3], s[16:17], 0, v[70:71]
	s_ashr_i32 vcc_hi, vcc_lo, 31
	v_lshl_add_u64 v[2:3], vcc, 2, v[2:3]
	v_lshlrev_b32_e32 v70, 2, v68
	v_lshl_add_u64 v[58:59], v[2:3], 0, v[70:71]
	v_add_co_u32_e32 v6, vcc, s64, v58
	s_lshl_b32 s4, s4, 7
	s_nop 0
	v_addc_co_u32_e32 v7, vcc, 0, v59, vcc
	v_add_co_u32_e32 v10, vcc, s80, v58
	global_load_dwordx4 v[2:5], v[58:59], off nt
	s_nop 0
	global_load_dwordx4 v[6:9], v[6:7], off nt
	v_addc_co_u32_e32 v11, vcc, 0, v59, vcc
	v_add_co_u32_e32 v14, vcc, s81, v58
	s_nop 1
	v_addc_co_u32_e32 v15, vcc, 0, v59, vcc
	v_add_co_u32_e32 v18, vcc, s67, v58
	global_load_dwordx4 v[10:13], v[10:11], off nt
	s_nop 0
	global_load_dwordx4 v[14:17], v[14:15], off nt
	v_addc_co_u32_e32 v19, vcc, 0, v59, vcc
	v_add_co_u32_e32 v22, vcc, s82, v58
	s_nop 1
	v_addc_co_u32_e32 v23, vcc, 0, v59, vcc
	v_add_co_u32_e32 v26, vcc, s83, v58
	global_load_dwordx4 v[18:21], v[18:19], off nt
	s_nop 0
	global_load_dwordx4 v[22:25], v[22:23], off nt
	v_addc_co_u32_e32 v27, vcc, 0, v59, vcc
	v_add_co_u32_e32 v30, vcc, s84, v58
	s_nop 1
	v_addc_co_u32_e32 v31, vcc, 0, v59, vcc
	v_add_co_u32_e32 v34, vcc, s71, v58
	global_load_dwordx4 v[26:29], v[26:27], off nt
	s_nop 0
	global_load_dwordx4 v[30:33], v[30:31], off nt
	v_addc_co_u32_e32 v35, vcc, 0, v59, vcc
	v_add_co_u32_e32 v38, vcc, s85, v58
	s_nop 1
	v_addc_co_u32_e32 v39, vcc, 0, v59, vcc
	v_add_co_u32_e32 v42, vcc, s86, v58
	global_load_dwordx4 v[34:37], v[34:35], off nt
	s_nop 0
	global_load_dwordx4 v[38:41], v[38:39], off nt
	v_addc_co_u32_e32 v43, vcc, 0, v59, vcc
	v_add_co_u32_e32 v46, vcc, s87, v58
	s_nop 1
	v_addc_co_u32_e32 v47, vcc, 0, v59, vcc
	v_add_co_u32_e32 v50, vcc, s73, v58
	global_load_dwordx4 v[42:45], v[42:43], off nt
	s_nop 0
	global_load_dwordx4 v[46:49], v[46:47], off nt
	v_addc_co_u32_e32 v51, vcc, 0, v59, vcc
	v_add_co_u32_e32 v54, vcc, s88, v58
	s_nop 1
	v_addc_co_u32_e32 v55, vcc, 0, v59, vcc
	v_add_co_u32_e32 v60, vcc, s89, v58
	global_load_dwordx4 v[50:53], v[50:51], off nt
	s_nop 0
	global_load_dwordx4 v[54:57], v[54:55], off nt
	v_addc_co_u32_e32 v61, vcc, 0, v59, vcc
	v_add_co_u32_e32 v62, vcc, s90, v58
	s_nop 1
	v_addc_co_u32_e32 v63, vcc, 0, v59, vcc
	global_load_dwordx4 v[58:61], v[60:61], off nt
	s_nop 0
	global_load_dwordx4 v[62:65], v[62:63], off nt
	s_waitcnt vmcnt(14)
	v_cvt_pk_bf16_f32 v2, v2, v6
	v_cvt_pk_bf16_f32 v3, v3, v7
	v_cvt_pk_bf16_f32 v4, v4, v8
	v_cvt_pk_bf16_f32 v5, v5, v9
	ds_write_b128 v94, v[2:5]
	s_waitcnt vmcnt(12)
	v_cvt_pk_bf16_f32 v2, v10, v14
	v_cvt_pk_bf16_f32 v3, v11, v15
	v_cvt_pk_bf16_f32 v4, v12, v16
	v_cvt_pk_bf16_f32 v5, v13, v17
	ds_write_b128 v94, v[2:5] offset:1088
	s_waitcnt vmcnt(10)
	v_cvt_pk_bf16_f32 v2, v18, v22
	v_cvt_pk_bf16_f32 v3, v19, v23
	v_cvt_pk_bf16_f32 v4, v20, v24
	v_cvt_pk_bf16_f32 v5, v21, v25
	ds_write_b128 v94, v[2:5] offset:2176
	s_waitcnt vmcnt(8)
	v_cvt_pk_bf16_f32 v2, v26, v30
	v_cvt_pk_bf16_f32 v3, v27, v31
	v_cvt_pk_bf16_f32 v4, v28, v32
	v_cvt_pk_bf16_f32 v5, v29, v33
	ds_write_b128 v94, v[2:5] offset:3264
	s_waitcnt vmcnt(6)
	v_cvt_pk_bf16_f32 v2, v34, v38
	v_cvt_pk_bf16_f32 v3, v35, v39
	v_cvt_pk_bf16_f32 v4, v36, v40
	v_cvt_pk_bf16_f32 v5, v37, v41
	ds_write_b128 v94, v[2:5] offset:4352
	s_waitcnt vmcnt(4)
	v_cvt_pk_bf16_f32 v2, v42, v46
	v_cvt_pk_bf16_f32 v3, v43, v47
	v_cvt_pk_bf16_f32 v4, v44, v48
	v_cvt_pk_bf16_f32 v5, v45, v49
	ds_write_b128 v94, v[2:5] offset:5440
	s_waitcnt vmcnt(2)
	v_cvt_pk_bf16_f32 v2, v50, v54
	v_cvt_pk_bf16_f32 v3, v51, v55
	v_cvt_pk_bf16_f32 v4, v52, v56
	v_cvt_pk_bf16_f32 v5, v53, v57
	ds_write_b128 v94, v[2:5] offset:6528
	s_waitcnt vmcnt(0)
	v_cvt_pk_bf16_f32 v2, v58, v62
	v_cvt_pk_bf16_f32 v3, v59, v63
	v_cvt_pk_bf16_f32 v4, v60, v64
	v_cvt_pk_bf16_f32 v5, v61, v65
	ds_write_b128 v94, v[2:5] offset:7616
	s_waitcnt lgkmcnt(0)
	v_add_u32_e32 v14, v95, v96
	ds_read_b128 v[2:5], v14
	ds_read_b128 v[6:9], v14 offset:272
	ds_read_b128 v[10:13], v14 offset:544
	ds_read_b128 v[14:17], v14 offset:816
	v_add_u32_e32 v18, s14, v147
	v_add_u32_e32 v24, 0x114000, v18
	v_ashrrev_i32_e32 v25, 31, v24
	v_lshl_add_u64 v[22:23], v[88:89], 0, s[4:5]
	s_waitcnt lgkmcnt(3)
	v_mov_b32_e32 v18, v2
	v_lshlrev_b64 v[24:25], 9, v[24:25]
	v_add_u32_e32 v2, s14, v146
	s_waitcnt lgkmcnt(2)
	v_mov_b32_e32 v19, v6
	s_waitcnt lgkmcnt(1)
	v_mov_b32_e32 v20, v10
	s_waitcnt lgkmcnt(0)
	v_mov_b32_e32 v21, v14
	v_lshl_add_u64 v[24:25], v[22:23], 0, v[24:25]
	v_add_u32_e32 v2, 0x114000, v2
	global_store_dwordx4 v[24:25], v[18:21], off
	v_mov_b32_e32 v14, v5
	s_nop 0
	v_mov_b32_e32 v18, v3
	v_ashrrev_i32_e32 v3, 31, v2
	v_lshlrev_b64 v[2:3], 9, v[2:3]
	v_mov_b32_e32 v19, v7
	v_mov_b32_e32 v20, v11
	v_mov_b32_e32 v21, v15
	v_lshl_add_u64 v[2:3], v[22:23], 0, v[2:3]
	global_store_dwordx4 v[2:3], v[18:21], off
	v_add_u32_e32 v2, s14, v145
	v_add_u32_e32 v2, 0x114000, v2
	v_ashrrev_i32_e32 v3, 31, v2
	v_lshlrev_b64 v[2:3], 9, v[2:3]
	v_mov_b32_e32 v18, v4
	v_mov_b32_e32 v19, v8
	v_mov_b32_e32 v20, v12
	v_mov_b32_e32 v21, v16
	v_lshl_add_u64 v[2:3], v[22:23], 0, v[2:3]
	global_store_dwordx4 v[2:3], v[18:21], off
	v_add_u32_e32 v2, s14, v144
	v_add_u32_e32 v2, 0x114000, v2
	v_ashrrev_i32_e32 v3, 31, v2
	v_lshlrev_b64 v[2:3], 9, v[2:3]
	v_mov_b32_e32 v15, v9
	v_mov_b32_e32 v16, v13
	v_lshl_add_u64 v[2:3], v[22:23], 0, v[2:3]
	global_store_dwordx4 v[2:3], v[14:17], off
	v_add_u32_e32 v18, s14, v143
	v_add_u32_e32 v24, 0x114000, v18
	v_add_u32_e32 v14, v98, v96
	ds_read_b128 v[2:5], v14
	ds_read_b128 v[6:9], v14 offset:272
	ds_read_b128 v[10:13], v14 offset:544
	ds_read_b128 v[14:17], v14 offset:816
	v_ashrrev_i32_e32 v25, 31, v24
	s_waitcnt lgkmcnt(3)
	v_mov_b32_e32 v18, v2
	v_lshlrev_b64 v[24:25], 9, v[24:25]
	v_add_u32_e32 v2, s14, v142
	s_waitcnt lgkmcnt(2)
	v_mov_b32_e32 v19, v6
	s_waitcnt lgkmcnt(1)
	v_mov_b32_e32 v20, v10
	s_waitcnt lgkmcnt(0)
	v_mov_b32_e32 v21, v14
	v_lshl_add_u64 v[24:25], v[22:23], 0, v[24:25]
	v_add_u32_e32 v2, 0x114000, v2
	global_store_dwordx4 v[24:25], v[18:21], off
	v_mov_b32_e32 v14, v5
	s_nop 0
	v_mov_b32_e32 v18, v3
	v_ashrrev_i32_e32 v3, 31, v2
	v_lshlrev_b64 v[2:3], 9, v[2:3]
	v_mov_b32_e32 v19, v7
	v_mov_b32_e32 v20, v11
	v_mov_b32_e32 v21, v15
	v_lshl_add_u64 v[2:3], v[22:23], 0, v[2:3]
	global_store_dwordx4 v[2:3], v[18:21], off
	v_add_u32_e32 v2, s14, v141
	v_add_u32_e32 v2, 0x114000, v2
	v_ashrrev_i32_e32 v3, 31, v2
	v_lshlrev_b64 v[2:3], 9, v[2:3]
	v_mov_b32_e32 v18, v4
	v_mov_b32_e32 v19, v8
	v_mov_b32_e32 v20, v12
	v_mov_b32_e32 v21, v16
	v_lshl_add_u64 v[2:3], v[22:23], 0, v[2:3]
	global_store_dwordx4 v[2:3], v[18:21], off
	v_add_u32_e32 v2, s14, v140
	v_add_u32_e32 v2, 0x114000, v2
	v_ashrrev_i32_e32 v3, 31, v2
	v_lshlrev_b64 v[2:3], 9, v[2:3]
	v_mov_b32_e32 v15, v9
	v_mov_b32_e32 v16, v13
	v_lshl_add_u64 v[2:3], v[22:23], 0, v[2:3]
	global_store_dwordx4 v[2:3], v[14:17], off
	s_waitcnt lgkmcnt(0)

.LBB0_57:
	s_andn2_b64 vcc, exec, s[14:15]
	s_cbranch_vccnz .LBB0_8
	s_ashr_i32 s4, s52, 31
	s_mov_b64 s[14:15], s[0:1]
	s_lshr_b32 s4, s4, 26
	s_load_dwordx2 vcc, s[14:15], 0x30
	s_add_i32 s4, s52, s4
	s_and_b32 s14, s4, 0xffffffc0
	s_lshl_b32 s4, s4, 6
	s_and_b32 s4, s4, 0xfffff000
	v_or_b32_e32 v2, s14, v67
	s_sub_i32 s15, s21, s4
	v_ashrrev_i32_e32 v3, 31, v2
	s_add_i32 s52, s15, 0x114000
	v_lshlrev_b64 v[2:3], 14, v[2:3]
	s_waitcnt lgkmcnt(0)
	v_lshl_add_u64 v[2:3], vcc, 0, v[2:3]
	s_ashr_i32 s53, s52, 31
	v_lshl_add_u64 v[2:3], s[52:53], 2, v[2:3]
	v_lshlrev_b32_e32 v70, 2, v68
	v_lshl_add_u64 v[2:3], v[2:3], 0, v[70:71]
	v_add_co_u32_e32 v4, vcc, s66, v2
	s_mov_b64 s[16:17], s[0:1]
	s_nop 0
	v_addc_co_u32_e32 v5, vcc, 0, v3, vcc
	global_load_dwordx4 v[58:61], v[2:3], off nt
	global_load_dwordx4 v[62:65], v[4:5], off nt
	v_add_co_u32_e32 v4, vcc, s67, v2
	s_nop 1
	v_addc_co_u32_e32 v5, vcc, 0, v3, vcc
	v_add_co_u32_e32 v6, vcc, s70, v2
	s_nop 1
	v_addc_co_u32_e32 v7, vcc, 0, v3, vcc
	global_load_dwordx4 v[50:53], v[4:5], off nt
	global_load_dwordx4 v[54:57], v[6:7], off nt
	v_add_co_u32_e32 v4, vcc, s71, v2
	s_nop 1
	v_addc_co_u32_e32 v5, vcc, 0, v3, vcc
	v_add_co_u32_e32 v6, vcc, s72, v2
	s_nop 1
	v_addc_co_u32_e32 v7, vcc, 0, v3, vcc
	global_load_dwordx4 v[42:45], v[4:5], off nt
	global_load_dwordx4 v[46:49], v[6:7], off nt
	v_add_co_u32_e32 v4, vcc, s73, v2
	s_nop 1
	v_addc_co_u32_e32 v5, vcc, 0, v3, vcc
	v_add_co_u32_e32 v6, vcc, s74, v2
	s_nop 1
	v_addc_co_u32_e32 v7, vcc, 0, v3, vcc
	global_load_dwordx4 v[34:37], v[4:5], off nt
	global_load_dwordx4 v[38:41], v[6:7], off nt
	v_add_co_u32_e32 v4, vcc, s75, v2
	s_nop 1
	v_addc_co_u32_e32 v5, vcc, 0, v3, vcc
	v_add_co_u32_e32 v6, vcc, s76, v2
	s_nop 1
	v_addc_co_u32_e32 v7, vcc, 0, v3, vcc
	global_load_dwordx4 v[22:25], v[4:5], off nt
	global_load_dwordx4 v[30:33], v[6:7], off nt
	v_add_co_u32_e32 v4, vcc, s77, v2
	s_nop 1
	v_addc_co_u32_e32 v5, vcc, 0, v3, vcc
	v_add_co_u32_e32 v6, vcc, s78, v2
	s_nop 1
	v_addc_co_u32_e32 v7, vcc, 0, v3, vcc
	global_load_dwordx4 v[14:17], v[4:5], off nt
	global_load_dwordx4 v[26:29], v[6:7], off nt
	v_add_co_u32_e32 v4, vcc, s79, v2
	s_nop 1
	v_addc_co_u32_e32 v5, vcc, 0, v3, vcc
	v_add_co_u32_e32 v10, vcc, 0xc4000, v2
	s_nop 1
	v_addc_co_u32_e32 v11, vcc, 0, v3, vcc
	global_load_dwordx4 v[6:9], v[4:5], off nt
	global_load_dwordx4 v[18:21], v[10:11], off nt
	v_add_co_u32_e32 v4, vcc, 0xe0000, v2
	s_nop 1
	v_addc_co_u32_e32 v5, vcc, 0, v3, vcc
	v_add_co_u32_e32 v10, vcc, 0xe4000, v2
	s_nop 1
	v_addc_co_u32_e32 v11, vcc, 0, v3, vcc
	global_load_dwordx4 v[2:5], v[4:5], off nt
	s_nop 0
	global_load_dwordx4 v[10:13], v[10:11], off nt
	s_load_dwordx2 s[16:17], s[16:17], 0x10
	s_waitcnt lgkmcnt(0)
	s_cmp_eq_u64 s[16:17], 0
	s_cbranch_scc1 .LBB0_7
	v_or_b32_e32 v148, s14, v93
	v_ashrrev_i32_e32 v149, 31, v148
	v_lshl_add_u64 v[148:149], v[148:149], 2, s[16:17]
	global_load_dwordx2 v[150:151], v[148:149], off
	global_load_dwordx2 v[152:153], v[148:149], off offset:32
	global_load_dwordx2 v[154:155], v[148:149], off offset:64
	global_load_dwordx2 v[156:157], v[148:149], off offset:96
	global_load_dwordx2 v[158:159], v[148:149], off offset:128
	global_load_dwordx2 v[160:161], v[148:149], off offset:160
	global_load_dwordx2 v[162:163], v[148:149], off offset:192
	s_nop 0
	global_load_dwordx2 v[148:149], v[148:149], off offset:224
	s_waitcnt vmcnt(7)
	v_pk_mul_f32 v[60:61], v[60:61], v[150:151] op_sel_hi:[1,0]
	v_pk_mul_f32 v[58:59], v[58:59], v[150:151] op_sel_hi:[1,0]
	v_pk_mul_f32 v[64:65], v[64:65], v[150:151] op_sel:[0,1]
	v_pk_mul_f32 v[62:63], v[62:63], v[150:151] op_sel:[0,1]
	s_waitcnt vmcnt(6)
	v_pk_mul_f32 v[52:53], v[52:53], v[152:153] op_sel_hi:[1,0]
	v_pk_mul_f32 v[50:51], v[50:51], v[152:153] op_sel_hi:[1,0]
	v_pk_mul_f32 v[56:57], v[56:57], v[152:153] op_sel:[0,1]
	v_pk_mul_f32 v[54:55], v[54:55], v[152:153] op_sel:[0,1]
	s_waitcnt vmcnt(5)
	v_pk_mul_f32 v[44:45], v[44:45], v[154:155] op_sel_hi:[1,0]
	v_pk_mul_f32 v[42:43], v[42:43], v[154:155] op_sel_hi:[1,0]
	v_pk_mul_f32 v[48:49], v[48:49], v[154:155] op_sel:[0,1]
	v_pk_mul_f32 v[46:47], v[46:47], v[154:155] op_sel:[0,1]
	s_waitcnt vmcnt(4)
	v_pk_mul_f32 v[36:37], v[36:37], v[156:157] op_sel_hi:[1,0]
	v_pk_mul_f32 v[34:35], v[34:35], v[156:157] op_sel_hi:[1,0]
	v_pk_mul_f32 v[40:41], v[40:41], v[156:157] op_sel:[0,1]
	v_pk_mul_f32 v[38:39], v[38:39], v[156:157] op_sel:[0,1]
	s_waitcnt vmcnt(3)
	v_pk_mul_f32 v[24:25], v[24:25], v[158:159] op_sel_hi:[1,0]
	v_pk_mul_f32 v[22:23], v[22:23], v[158:159] op_sel_hi:[1,0]
	v_pk_mul_f32 v[32:33], v[32:33], v[158:159] op_sel:[0,1]
	v_pk_mul_f32 v[30:31], v[30:31], v[158:159] op_sel:[0,1]
	s_waitcnt vmcnt(2)
	v_pk_mul_f32 v[16:17], v[16:17], v[160:161] op_sel_hi:[1,0]
	v_pk_mul_f32 v[14:15], v[14:15], v[160:161] op_sel_hi:[1,0]
	v_pk_mul_f32 v[28:29], v[28:29], v[160:161] op_sel:[0,1]
	v_pk_mul_f32 v[26:27], v[26:27], v[160:161] op_sel:[0,1]
	s_waitcnt vmcnt(1)
	v_pk_mul_f32 v[8:9], v[8:9], v[162:163] op_sel_hi:[1,0]
	v_pk_mul_f32 v[6:7], v[6:7], v[162:163] op_sel_hi:[1,0]
	v_pk_mul_f32 v[20:21], v[20:21], v[162:163] op_sel:[0,1]
	v_pk_mul_f32 v[18:19], v[18:19], v[162:163] op_sel:[0,1]
	s_waitcnt vmcnt(0)
	v_pk_mul_f32 v[4:5], v[4:5], v[148:149] op_sel_hi:[1,0]
	v_pk_mul_f32 v[2:3], v[2:3], v[148:149] op_sel_hi:[1,0]
	v_pk_mul_f32 v[12:13], v[12:13], v[148:149] op_sel:[0,1]
	v_pk_mul_f32 v[10:11], v[10:11], v[148:149] op_sel:[0,1]
	s_branch .LBB0_7
